# v32 + non-temporal loads/stores in the filler items (transposes, combine)
# baseline (speedup 1.0000x reference)
; DI unsigned cvt_pk_bf16(float lo, float hi) { unsigned r; asm("v_cvt_pk_bf16_f32 %0, %1, %2" : "=v"(r) : "v"(lo), "v"(hi)); return r; }
; DI void transpose_w(const float* __restrict__ W, int K, int N, bf16_t* __restrict__ Wt, int gtid, int gthreads) {
;   const int total = (K / 8) * N;
;   for (int id = gtid; id < total; id += gthreads) {
;     const int kc = id / N, n = id - kc * N;
;     const int rho = n & 255;
;     const int act = (n & ~255) + ((rho >> 5) & 3) * 64 + (rho >> 7) * 32 + ((rho >> 2) & 3) * 8 + ((rho >> 4) & 1) * 4 + (rho & 3);
;     const float* src = W + (size_t)(kc * 8) * N + act;
;     float v[8];
; #pragma unroll
;     for (int j = 0; j < 8; ++j) v[j] = src[(size_t)j * N];
;     uint4 o; o.x = cvt_pk_bf16(v[0], v[1]); o.y = cvt_pk_bf16(v[2], v[3]); o.z = cvt_pk_bf16(v[4], v[5]); o.w = cvt_pk_bf16(v[6], v[7]);
;     *(uint4*)(Wt + (size_t)n * K + kc * 8) = o;
;   }
.Ltq_item:
	v_readlane_b32 s4, v236, 20
	v_readlane_b32 s5, v236, 21
	s_sub_i32 s3, s12, 2096
	s_and_b32 s13, s3, 0xff
	v_lshl_add_u32 v0, s13, 9, v202
	s_nop 3
	s_load_dwordx2 s[6:7], s[4:5], 0x50
	s_load_dwordx4 s[8:11], s[4:5], 0x60
	v_and_b32_e32 v1, 0x3ff, v0
	v_lshrrev_b32_e32 v2, 10, v0
	v_and_b32_e32 v3, 0xffffff03, v1
	v_and_b32_e32 v9, 0x60, v1
	v_lshl_or_b32 v3, v9, 1, v3
	v_and_b32_e32 v9, 0x0c, v1
	v_lshl_or_b32 v3, v9, 1, v3
	v_bfe_u32 v9, v1, 7, 1
	v_lshl_or_b32 v3, v9, 5, v3
	v_bfe_u32 v9, v1, 4, 1
	v_lshl_or_b32 v3, v9, 2, v3
	v_lshlrev_b32_e32 v3, 2, v3
	v_lshl_or_b32 v3, v2, 15, v3
	v_lshlrev_b32_e32 v2, 4, v2
	v_lshl_or_b32 v4, v1, 11, v2
	v_lshl_or_b32 v5, v1, 13, v2
	v_add_u32_e32 v4, 0x800000, v4
	v_add_u32_e32 v5, 0x1200000, v5
	v_and_b32_e32 v1, 0xfff, v0
	v_lshrrev_b32_e32 v2, 12, v0
	v_and_b32_e32 v6, 0xffffff03, v1
	v_and_b32_e32 v9, 0x60, v1
	v_lshl_or_b32 v6, v9, 1, v6
	v_and_b32_e32 v9, 0x0c, v1
	v_lshl_or_b32 v6, v9, 1, v6
	v_bfe_u32 v9, v1, 7, 1
	v_lshl_or_b32 v6, v9, 5, v6
	v_bfe_u32 v9, v1, 4, 1
	v_lshl_or_b32 v6, v9, 2, v6
	v_lshlrev_b32_e32 v6, 2, v6
	v_lshl_or_b32 v6, v2, 17, v6
	v_lshlrev_b32_e32 v2, 4, v2
	v_lshl_or_b32 v7, v1, 11, v2
	v_add_u32_e32 v7, 0xa00000, v7
	s_waitcnt lgkmcnt(0)
	s_cmpk_gt_u32 s3, 0xff
	s_cbranch_scc1 .Ltq_second
	global_load_dword v16, v3, s[6:7] nt
	v_add_u32_e32 v49, 0x1000, v3
	global_load_dword v17, v49, s[6:7] nt
	v_add_u32_e32 v50, 0x2000, v3
	global_load_dword v18, v50, s[6:7] nt
	v_add_u32_e32 v51, 0x3000, v3
	global_load_dword v19, v51, s[6:7] nt
	v_add_u32_e32 v52, 0x4000, v3
	global_load_dword v20, v52, s[6:7] nt
	v_add_u32_e32 v53, 0x5000, v3
	global_load_dword v21, v53, s[6:7] nt
	v_add_u32_e32 v54, 0x6000, v3
	global_load_dword v22, v54, s[6:7] nt
	v_add_u32_e32 v55, 0x7000, v3
	global_load_dword v23, v55, s[6:7] nt
	global_load_dword v24, v6, s[8:9] nt
	v_add_u32_e32 v49, 0x4000, v6
	global_load_dword v25, v49, s[8:9] nt
	v_add_u32_e32 v50, 0x8000, v6
	global_load_dword v26, v50, s[8:9] nt
	v_add_u32_e32 v51, 0xc000, v6
	global_load_dword v27, v51, s[8:9] nt
	v_add_u32_e32 v52, 0x10000, v6
	global_load_dword v28, v52, s[8:9] nt
	v_add_u32_e32 v53, 0x14000, v6
	global_load_dword v29, v53, s[8:9] nt
	v_add_u32_e32 v54, 0x18000, v6
	global_load_dword v30, v54, s[8:9] nt
	v_add_u32_e32 v55, 0x1c000, v6
	global_load_dword v31, v55, s[8:9] nt
	v_add_u32_e32 v48, 0x400000, v6
	global_load_dword v32, v48, s[8:9] nt
	v_add_u32_e32 v49, 0x404000, v6
	global_load_dword v33, v49, s[8:9] nt
	v_add_u32_e32 v50, 0x408000, v6
	global_load_dword v34, v50, s[8:9] nt
	v_add_u32_e32 v51, 0x40c000, v6
	global_load_dword v35, v51, s[8:9] nt
	v_add_u32_e32 v52, 0x410000, v6
	global_load_dword v36, v52, s[8:9] nt
	v_add_u32_e32 v53, 0x414000, v6
	global_load_dword v37, v53, s[8:9] nt
	v_add_u32_e32 v54, 0x418000, v6
	global_load_dword v38, v54, s[8:9] nt
	v_add_u32_e32 v55, 0x41c000, v6
	global_load_dword v39, v55, s[8:9] nt
	v_add_u32_e32 v48, 0x800000, v6
	global_load_dword v40, v48, s[8:9] nt
	v_add_u32_e32 v49, 0x804000, v6
	global_load_dword v41, v49, s[8:9] nt
	v_add_u32_e32 v50, 0x808000, v6
	global_load_dword v42, v50, s[8:9] nt
	v_add_u32_e32 v51, 0x80c000, v6
	global_load_dword v43, v51, s[8:9] nt
	v_add_u32_e32 v52, 0x810000, v6
	global_load_dword v44, v52, s[8:9] nt
	v_add_u32_e32 v53, 0x814000, v6
	global_load_dword v45, v53, s[8:9] nt
	v_add_u32_e32 v54, 0x818000, v6
	global_load_dword v46, v54, s[8:9] nt
	v_add_u32_e32 v55, 0x81c000, v6
	global_load_dword v47, v55, s[8:9] nt
	s_waitcnt vmcnt(24)
	v_cvt_pk_bf16_f32 v56, v16, v17
	v_cvt_pk_bf16_f32 v57, v18, v19
	v_cvt_pk_bf16_f32 v58, v20, v21
	v_cvt_pk_bf16_f32 v59, v22, v23
	global_store_dwordx4 v4, v[56:59], s[58:59] nt
	v_add_u32_e32 v48, 0xc00000, v6
	global_load_dword v16, v48, s[8:9] nt
	v_add_u32_e32 v49, 0xc04000, v6
	global_load_dword v17, v49, s[8:9] nt
	v_add_u32_e32 v50, 0xc08000, v6
	global_load_dword v18, v50, s[8:9] nt
	v_add_u32_e32 v51, 0xc0c000, v6
	global_load_dword v19, v51, s[8:9] nt
	v_add_u32_e32 v52, 0xc10000, v6
	global_load_dword v20, v52, s[8:9] nt
	v_add_u32_e32 v53, 0xc14000, v6
	global_load_dword v21, v53, s[8:9] nt
	v_add_u32_e32 v54, 0xc18000, v6
	global_load_dword v22, v54, s[8:9] nt
	v_add_u32_e32 v55, 0xc1c000, v6
	global_load_dword v23, v55, s[8:9] nt
	s_waitcnt vmcnt(25)
	v_cvt_pk_bf16_f32 v60, v24, v25
	v_cvt_pk_bf16_f32 v61, v26, v27
	v_cvt_pk_bf16_f32 v62, v28, v29
	v_cvt_pk_bf16_f32 v63, v30, v31
	global_store_dwordx4 v7, v[60:63], s[58:59] nt
	s_waitcnt vmcnt(18)
	v_cvt_pk_bf16_f32 v56, v32, v33
	v_cvt_pk_bf16_f32 v57, v34, v35
	v_cvt_pk_bf16_f32 v58, v36, v37
	v_cvt_pk_bf16_f32 v59, v38, v39
	v_add_u32_e32 v10, 0x200, v7
	global_store_dwordx4 v10, v[56:59], s[58:59] nt
	s_waitcnt vmcnt(11)
	v_cvt_pk_bf16_f32 v60, v40, v41
	v_cvt_pk_bf16_f32 v61, v42, v43
	v_cvt_pk_bf16_f32 v62, v44, v45
	v_cvt_pk_bf16_f32 v63, v46, v47
	v_add_u32_e32 v10, 0x400, v7
	global_store_dwordx4 v10, v[60:63], s[58:59] nt
	s_waitcnt vmcnt(3)
	v_cvt_pk_bf16_f32 v56, v16, v17
	v_cvt_pk_bf16_f32 v57, v18, v19
	v_cvt_pk_bf16_f32 v58, v20, v21
	v_cvt_pk_bf16_f32 v59, v22, v23
	v_add_u32_e32 v10, 0x600, v7
	global_store_dwordx4 v10, v[56:59], s[58:59] nt
	s_branch .LBB0_952
; DI unsigned cvt_pk_bf16(float lo, float hi) { unsigned r; asm("v_cvt_pk_bf16_f32 %0, %1, %2" : "=v"(r) : "v"(lo), "v"(hi)); return r; }
; DI void transpose_w(const float* __restrict__ W, int K, int N, bf16_t* __restrict__ Wt, int gtid, int gthreads) {
;   const int total = (K / 8) * N;
;   for (int id = gtid; id < total; id += gthreads) {
;     const int kc = id / N, n = id - kc * N;
;     const int rho = n & 255;
;     const int act = (n & ~255) + ((rho >> 5) & 3) * 64 + (rho >> 7) * 32 + ((rho >> 2) & 3) * 8 + ((rho >> 4) & 1) * 4 + (rho & 3);
;     const float* src = W + (size_t)(kc * 8) * N + act;
;     float v[8];
; #pragma unroll
;     for (int j = 0; j < 8; ++j) v[j] = src[(size_t)j * N];
;     uint4 o; o.x = cvt_pk_bf16(v[0], v[1]); o.y = cvt_pk_bf16(v[2], v[3]); o.z = cvt_pk_bf16(v[4], v[5]); o.w = cvt_pk_bf16(v[6], v[7]);
;     *(uint4*)(Wt + (size_t)n * K + kc * 8) = o;
;   }
.Ltq_second:
	global_load_dword v16, v3, s[10:11] nt
	v_add_u32_e32 v49, 0x1000, v3
	global_load_dword v17, v49, s[10:11] nt
	v_add_u32_e32 v50, 0x2000, v3
	global_load_dword v18, v50, s[10:11] nt
	v_add_u32_e32 v51, 0x3000, v3
	global_load_dword v19, v51, s[10:11] nt
	v_add_u32_e32 v52, 0x4000, v3
	global_load_dword v20, v52, s[10:11] nt
	v_add_u32_e32 v53, 0x5000, v3
	global_load_dword v21, v53, s[10:11] nt
	v_add_u32_e32 v54, 0x6000, v3
	global_load_dword v22, v54, s[10:11] nt
	v_add_u32_e32 v55, 0x7000, v3
	global_load_dword v23, v55, s[10:11] nt
	v_add_u32_e32 v48, 0x400000, v3
	global_load_dword v24, v48, s[10:11] nt
	v_add_u32_e32 v49, 0x401000, v3
	global_load_dword v25, v49, s[10:11] nt
	v_add_u32_e32 v50, 0x402000, v3
	global_load_dword v26, v50, s[10:11] nt
	v_add_u32_e32 v51, 0x403000, v3
	global_load_dword v27, v51, s[10:11] nt
	v_add_u32_e32 v52, 0x404000, v3
	global_load_dword v28, v52, s[10:11] nt
	v_add_u32_e32 v53, 0x405000, v3
	global_load_dword v29, v53, s[10:11] nt
	v_add_u32_e32 v54, 0x406000, v3
	global_load_dword v30, v54, s[10:11] nt
	v_add_u32_e32 v55, 0x407000, v3
	global_load_dword v31, v55, s[10:11] nt
	v_add_u32_e32 v48, 0x800000, v3
	global_load_dword v32, v48, s[10:11] nt
	v_add_u32_e32 v49, 0x801000, v3
	global_load_dword v33, v49, s[10:11] nt
	v_add_u32_e32 v50, 0x802000, v3
	global_load_dword v34, v50, s[10:11] nt
	v_add_u32_e32 v51, 0x803000, v3
	global_load_dword v35, v51, s[10:11] nt
	v_add_u32_e32 v52, 0x804000, v3
	global_load_dword v36, v52, s[10:11] nt
	v_add_u32_e32 v53, 0x805000, v3
	global_load_dword v37, v53, s[10:11] nt
	v_add_u32_e32 v54, 0x806000, v3
	global_load_dword v38, v54, s[10:11] nt
	v_add_u32_e32 v55, 0x807000, v3
	global_load_dword v39, v55, s[10:11] nt
	v_add_u32_e32 v48, 0xc00000, v3
	global_load_dword v40, v48, s[10:11] nt
	v_add_u32_e32 v49, 0xc01000, v3
	global_load_dword v41, v49, s[10:11] nt
	v_add_u32_e32 v50, 0xc02000, v3
	global_load_dword v42, v50, s[10:11] nt
	v_add_u32_e32 v51, 0xc03000, v3
	global_load_dword v43, v51, s[10:11] nt
	v_add_u32_e32 v52, 0xc04000, v3
	global_load_dword v44, v52, s[10:11] nt
	v_add_u32_e32 v53, 0xc05000, v3
	global_load_dword v45, v53, s[10:11] nt
	v_add_u32_e32 v54, 0xc06000, v3
	global_load_dword v46, v54, s[10:11] nt
	v_add_u32_e32 v55, 0xc07000, v3
	global_load_dword v47, v55, s[10:11] nt
	s_waitcnt vmcnt(24)
	v_cvt_pk_bf16_f32 v56, v16, v17
	v_cvt_pk_bf16_f32 v57, v18, v19
	v_cvt_pk_bf16_f32 v58, v20, v21
	v_cvt_pk_bf16_f32 v59, v22, v23
	global_store_dwordx4 v5, v[56:59], s[58:59] nt
	s_waitcnt vmcnt(17)
	v_cvt_pk_bf16_f32 v60, v24, v25
	v_cvt_pk_bf16_f32 v61, v26, v27
	v_cvt_pk_bf16_f32 v62, v28, v29
	v_cvt_pk_bf16_f32 v63, v30, v31
	v_add_u32_e32 v10, 0x800, v5
	global_store_dwordx4 v10, v[60:63], s[58:59] nt
	s_waitcnt vmcnt(10)
	v_cvt_pk_bf16_f32 v56, v32, v33
	v_cvt_pk_bf16_f32 v57, v34, v35
	v_cvt_pk_bf16_f32 v58, v36, v37
	v_cvt_pk_bf16_f32 v59, v38, v39
	v_add_u32_e32 v10, 0x1000, v5
	global_store_dwordx4 v10, v[56:59], s[58:59] nt
	s_waitcnt vmcnt(3)
	v_cvt_pk_bf16_f32 v60, v40, v41
	v_cvt_pk_bf16_f32 v61, v42, v43
	v_cvt_pk_bf16_f32 v62, v44, v45
	v_cvt_pk_bf16_f32 v63, v46, v47
	v_add_u32_e32 v10, 0x1800, v5
	global_store_dwordx4 v10, v[60:63], s[58:59] nt
	s_branch .LBB0_952

; DI void phase_combine(const Params& p) {
;   const int lane = threadIdx.x & 63, wave = threadIdx.x >> 6;
;   const unsigned* ofw = (const unsigned*)p.out; const unsigned* obw = (const unsigned*)((const bf16_t*)p.out + (size_t)NTOK * 512);
;   const unsigned* GH = (const unsigned*)(p.ws + WS_GH);
;   bf16_t* OC = (bf16_t*)(p.ws + WS_OCAT);
;   const float w0 = p.hgrn_norm_w[lane * 2], w1 = p.hgrn_norm_w[lane * 2 + 1];
;   for (int tok = blockIdx.x * 8 + wave; tok < NTOK; tok += gridDim.x * 8) {
;     unsigned a[4], b[4], g[4];
; #pragma unroll
;     for (int hh = 0; hh < 4; ++hh) { const size_t idx = ((size_t)tok * 512 + hh * 128 + lane * 2) >> 1; a[hh] = ofw[idx]; b[hh] = obw[idx]; g[hh] = GH[idx]; }
.Lcq_go:
	s_or_b64 exec, exec, s[0:1]
	s_barrier
	s_sub_i32 s3, s12, 2608
	s_lshl_b32 s3, s3, 7
	v_lshrrev_b32_e32 v0, 6, v202
	v_add_u32_e32 v0, s3, v0
	v_and_b32_e32 v4, 0x7e, v203
	v_lshlrev_b32_e32 v1, 2, v4
	global_load_dwordx2 v[2:3], v1, s[46:47]
	s_add_u32 s6, s56, 0x4000000
	s_addc_u32 s7, s57, 0
	s_add_u32 s8, s58, 0x26000000
	s_addc_u32 s9, s59, 0
	v_cmp_lt_i32_e32 vcc, v206, v205
	s_nop 1
	v_cndmask_b32_e32 v1, v204, v206, vcc
	v_lshlrev_b32_e32 v8, 2, v1
	v_cmp_lt_i32_e32 vcc, v207, v205
	s_nop 1
	v_cndmask_b32_e32 v1, v204, v207, vcc
	v_lshlrev_b32_e32 v9, 2, v1
	v_cmp_lt_i32_e32 vcc, v211, v205
	s_nop 1
	v_cndmask_b32_e32 v1, v204, v211, vcc
	v_lshlrev_b32_e32 v10, 2, v1
	v_cmp_lt_i32_e32 vcc, v210, v205
	s_nop 1
	v_cndmask_b32_e32 v1, v204, v210, vcc
	v_lshlrev_b32_e32 v11, 2, v1
	v_cmp_lt_i32_e32 vcc, v209, v205
	s_nop 1
	v_cndmask_b32_e32 v1, v204, v209, vcc
	v_lshlrev_b32_e32 v12, 2, v1
	v_cmp_lt_i32_e32 vcc, v208, v205
	s_nop 1
	v_cndmask_b32_e32 v1, v204, v208, vcc
	v_lshlrev_b32_e32 v13, 2, v1
	v_mov_b32_e32 v5, 0
	v_lshlrev_b32_e32 v4, 1, v4
	s_mov_b64 s[12:13], 0x2a000400
	s_mov_b64 s[10:11], 0x2000
	s_mov_b64 s[16:17], 0x4000
	v_mov_b32_e32 v14, 0x358637bd
	s_mov_b32 s14, 0x800000
	v_ashrrev_i32_e32 v1, 31, v0
	v_lshlrev_b64 v[90:91], 10, v[0:1]
	v_or_b32_e32 v90, v90, v4
	v_lshl_add_u64 v[92:93], s[56:57], 0, v[90:91]
	v_lshl_add_u64 v[94:95], s[6:7], 0, v[90:91]
	v_lshl_add_u64 v[96:97], s[8:9], 0, v[90:91]
	v_lshlrev_b64 v[98:99], 11, v[0:1]
	v_lshl_add_u64 v[98:99], s[58:59], 0, v[98:99]
	v_lshl_add_u64 v[98:99], v[98:99], 0, v[4:5]
	v_lshl_add_u64 v[98:99], v[98:99], 0, s[12:13]
	global_load_dword v104, v[92:93], off nt
	global_load_dword v105, v[92:93], off offset:256 nt
	global_load_dword v106, v[92:93], off offset:512 nt
	global_load_dword v107, v[92:93], off offset:768 nt
	global_load_dword v108, v[94:95], off nt
	global_load_dword v109, v[94:95], off offset:256 nt
	global_load_dword v110, v[94:95], off offset:512 nt
	global_load_dword v111, v[94:95], off offset:768 nt
	global_load_dword v112, v[96:97], off nt
	global_load_dword v113, v[96:97], off offset:256 nt
	global_load_dword v114, v[96:97], off offset:512 nt
	global_load_dword v115, v[96:97], off offset:768 nt
	v_lshl_add_u64 v[92:93], v[92:93], 0, s[10:11]
	v_lshl_add_u64 v[94:95], v[94:95], 0, s[10:11]
	v_lshl_add_u64 v[96:97], v[96:97], 0, s[10:11]
	global_load_dword v116, v[92:93], off nt
	global_load_dword v117, v[92:93], off offset:256 nt
	global_load_dword v118, v[92:93], off offset:512 nt
	global_load_dword v119, v[92:93], off offset:768 nt
	global_load_dword v120, v[94:95], off nt
	global_load_dword v121, v[94:95], off offset:256 nt
	global_load_dword v122, v[94:95], off offset:512 nt
	global_load_dword v123, v[94:95], off offset:768 nt
	global_load_dword v124, v[96:97], off nt
	global_load_dword v125, v[96:97], off offset:256 nt
	global_load_dword v126, v[96:97], off offset:512 nt
	global_load_dword v127, v[96:97], off offset:768 nt
	v_lshl_add_u64 v[92:93], v[92:93], 0, s[10:11]
	v_lshl_add_u64 v[94:95], v[94:95], 0, s[10:11]
	v_lshl_add_u64 v[96:97], v[96:97], 0, s[10:11]
	global_load_dword v128, v[92:93], off nt
	global_load_dword v129, v[92:93], off offset:256 nt
	global_load_dword v130, v[92:93], off offset:512 nt
	global_load_dword v131, v[92:93], off offset:768 nt
	global_load_dword v132, v[94:95], off nt
	global_load_dword v133, v[94:95], off offset:256 nt
	global_load_dword v134, v[94:95], off offset:512 nt
	global_load_dword v135, v[94:95], off offset:768 nt
	global_load_dword v136, v[96:97], off nt
	global_load_dword v137, v[96:97], off offset:256 nt
	global_load_dword v138, v[96:97], off offset:512 nt
	global_load_dword v139, v[96:97], off offset:768 nt
	v_lshl_add_u64 v[92:93], v[92:93], 0, s[10:11]
	v_lshl_add_u64 v[94:95], v[94:95], 0, s[10:11]
	v_lshl_add_u64 v[96:97], v[96:97], 0, s[10:11]
	global_load_dword v140, v[92:93], off nt
	global_load_dword v141, v[92:93], off offset:256 nt
	global_load_dword v142, v[92:93], off offset:512 nt
	global_load_dword v143, v[92:93], off offset:768 nt
	global_load_dword v144, v[94:95], off nt
	global_load_dword v145, v[94:95], off offset:256 nt
	global_load_dword v146, v[94:95], off offset:512 nt
	global_load_dword v147, v[94:95], off offset:768 nt
	global_load_dword v148, v[96:97], off nt
	global_load_dword v149, v[96:97], off offset:256 nt
	global_load_dword v150, v[96:97], off offset:512 nt
	global_load_dword v151, v[96:97], off offset:768 nt
	v_lshl_add_u64 v[92:93], v[92:93], 0, s[10:11]
	v_lshl_add_u64 v[94:95], v[94:95], 0, s[10:11]
	v_lshl_add_u64 v[96:97], v[96:97], 0, s[10:11]
	s_mov_b32 s98, 3
; DI unsigned cvt_pk_bf16(float lo, float hi) { unsigned r; asm("v_cvt_pk_bf16_f32 %0, %1, %2" : "=v"(r) : "v"(lo), "v"(hi)); return r; }
; DI void phase_combine(const Params& p) {
;     ...
;   for (int tok = blockIdx.x * 8 + wave; tok < NTOK; tok += gridDim.x * 8) {
;     unsigned a[4], b[4], g[4];
; #pragma unroll
;     for (int hh = 0; hh < 4; ++hh) { const size_t idx = ((size_t)tok * 512 + hh * 128 + lane * 2) >> 1; a[hh] = ofw[idx]; b[hh] = obw[idx]; g[hh] = GH[idx]; }
; #pragma unroll
;     for (int hh = 0; hh < 4; ++hh) {
;       const float o0 = __uint_as_float(a[hh] << 16) + __uint_as_float(b[hh] << 16), o1 = __uint_as_float(a[hh] & 0xffff0000u) + __uint_as_float(b[hh] & 0xffff0000u);
;       const float ss = wave_sum(o0 * o0 + o1 * o1);
;       const float rstd = rsqrtf(ss * (1.f / 128.f) + EPSN);
;       const float g0 = __uint_as_float(g[hh] << 16), g1 = __uint_as_float(g[hh] & 0xffff0000u);
;       *(unsigned*)(OC + (size_t)tok * 1024 + 512 + hh * 128 + lane * 2) = cvt_pk_bf16(o0 * rstd * w0 * g0, o1 * rstd * w1 * g1);
;     }
.Lcq_loop:
	s_waitcnt vmcnt(36)
	v_lshlrev_b32_e32 v64, 16, v104
	v_lshlrev_b32_e32 v76, 16, v108
	v_and_b32_e32 v68, 0xffff0000, v104
	v_and_b32_e32 v80, 0xffff0000, v108
	v_add_f32_e32 v64, v64, v76
	v_add_f32_e32 v68, v68, v80
	v_mul_f32_e32 v72, v64, v64
	v_mul_f32_e32 v76, v68, v68
	v_add_f32_e32 v72, v72, v76
	v_lshlrev_b32_e32 v65, 16, v105
	v_lshlrev_b32_e32 v77, 16, v109
	v_and_b32_e32 v69, 0xffff0000, v105
	v_and_b32_e32 v81, 0xffff0000, v109
	v_add_f32_e32 v65, v65, v77
	v_add_f32_e32 v69, v69, v81
	v_mul_f32_e32 v73, v65, v65
	v_mul_f32_e32 v77, v69, v69
	v_add_f32_e32 v73, v73, v77
	v_lshlrev_b32_e32 v66, 16, v106
	v_lshlrev_b32_e32 v78, 16, v110
	v_and_b32_e32 v70, 0xffff0000, v106
	v_and_b32_e32 v82, 0xffff0000, v110
	v_add_f32_e32 v66, v66, v78
	v_add_f32_e32 v70, v70, v82
	v_mul_f32_e32 v74, v66, v66
	v_mul_f32_e32 v78, v70, v70
	v_add_f32_e32 v74, v74, v78
	v_lshlrev_b32_e32 v67, 16, v107
	v_lshlrev_b32_e32 v79, 16, v111
	v_and_b32_e32 v71, 0xffff0000, v107
	v_and_b32_e32 v83, 0xffff0000, v111
	v_add_f32_e32 v67, v67, v79
	v_add_f32_e32 v71, v71, v83
	v_mul_f32_e32 v75, v67, v67
	v_mul_f32_e32 v79, v71, v71
	v_add_f32_e32 v75, v75, v79
	ds_bpermute_b32 v76, v8, v72
	ds_bpermute_b32 v77, v8, v73
	ds_bpermute_b32 v78, v8, v74
	ds_bpermute_b32 v79, v8, v75
	s_waitcnt lgkmcnt(3)
	v_add_f32_e32 v72, v72, v76
	s_waitcnt lgkmcnt(2)
	v_add_f32_e32 v73, v73, v77
	s_waitcnt lgkmcnt(1)
	v_add_f32_e32 v74, v74, v78
	s_waitcnt lgkmcnt(0)
	v_add_f32_e32 v75, v75, v79
	ds_bpermute_b32 v76, v9, v72
	ds_bpermute_b32 v77, v9, v73
	ds_bpermute_b32 v78, v9, v74
	ds_bpermute_b32 v79, v9, v75
	s_waitcnt lgkmcnt(3)
	v_add_f32_e32 v72, v72, v76
	s_waitcnt lgkmcnt(2)
	v_add_f32_e32 v73, v73, v77
	s_waitcnt lgkmcnt(1)
	v_add_f32_e32 v74, v74, v78
	s_waitcnt lgkmcnt(0)
	v_add_f32_e32 v75, v75, v79
	ds_bpermute_b32 v76, v10, v72
	ds_bpermute_b32 v77, v10, v73
	ds_bpermute_b32 v78, v10, v74
	ds_bpermute_b32 v79, v10, v75
	s_waitcnt lgkmcnt(3)
	v_add_f32_e32 v72, v72, v76
	s_waitcnt lgkmcnt(2)
	v_add_f32_e32 v73, v73, v77
	s_waitcnt lgkmcnt(1)
	v_add_f32_e32 v74, v74, v78
	s_waitcnt lgkmcnt(0)
	v_add_f32_e32 v75, v75, v79
	ds_bpermute_b32 v76, v11, v72
	ds_bpermute_b32 v77, v11, v73
	ds_bpermute_b32 v78, v11, v74
	ds_bpermute_b32 v79, v11, v75
	s_waitcnt lgkmcnt(3)
	v_add_f32_e32 v72, v72, v76
	s_waitcnt lgkmcnt(2)
	v_add_f32_e32 v73, v73, v77
	s_waitcnt lgkmcnt(1)
	v_add_f32_e32 v74, v74, v78
	s_waitcnt lgkmcnt(0)
	v_add_f32_e32 v75, v75, v79
	ds_bpermute_b32 v76, v12, v72
	ds_bpermute_b32 v77, v12, v73
	ds_bpermute_b32 v78, v12, v74
	ds_bpermute_b32 v79, v12, v75
	s_waitcnt lgkmcnt(3)
	v_add_f32_e32 v72, v72, v76
	s_waitcnt lgkmcnt(2)
	v_add_f32_e32 v73, v73, v77
	s_waitcnt lgkmcnt(1)
	v_add_f32_e32 v74, v74, v78
	s_waitcnt lgkmcnt(0)
	v_add_f32_e32 v75, v75, v79
	ds_bpermute_b32 v76, v13, v72
	ds_bpermute_b32 v77, v13, v73
	ds_bpermute_b32 v78, v13, v74
	ds_bpermute_b32 v79, v13, v75
	s_waitcnt lgkmcnt(3)
	v_add_f32_e32 v72, v72, v76
	s_waitcnt lgkmcnt(2)
	v_add_f32_e32 v73, v73, v77
	s_waitcnt lgkmcnt(1)
	v_add_f32_e32 v74, v74, v78
	s_waitcnt lgkmcnt(0)
	v_add_f32_e32 v75, v75, v79
	v_fmamk_f32 v80, v72, 0x3c000000, v14
	v_mul_f32_e32 v76, 0x4b800000, v80
	v_cmp_gt_f32_e32 vcc, s14, v80
	s_nop 1
	v_cndmask_b32_e32 v80, v80, v76, vcc
	v_rsq_f32_e32 v80, v80
	s_nop 0
	v_mul_f32_e32 v76, 0x45800000, v80
	v_cndmask_b32_e32 v80, v80, v76, vcc
	v_mul_f32_e32 v64, v64, v80
	v_mul_f32_e32 v68, v68, v80
	v_mul_f32_e32 v64, v2, v64
	v_mul_f32_e32 v68, v3, v68
	v_lshlrev_b32_e32 v76, 16, v112
	v_and_b32_e32 v72, 0xffff0000, v112
	v_mul_f32_e32 v64, v64, v76
	v_mul_f32_e32 v68, v68, v72
	v_cvt_pk_bf16_f32 v64, v64, v68
	global_store_dword v[98:99], v64, off nt
	v_fmamk_f32 v81, v73, 0x3c000000, v14
	v_mul_f32_e32 v77, 0x4b800000, v81
	v_cmp_gt_f32_e32 vcc, s14, v81
	s_nop 1
	v_cndmask_b32_e32 v81, v81, v77, vcc
	v_rsq_f32_e32 v81, v81
	s_nop 0
	v_mul_f32_e32 v77, 0x45800000, v81
	v_cndmask_b32_e32 v81, v81, v77, vcc
	v_mul_f32_e32 v65, v65, v81
	v_mul_f32_e32 v69, v69, v81
	v_mul_f32_e32 v65, v2, v65
	v_mul_f32_e32 v69, v3, v69
	v_lshlrev_b32_e32 v77, 16, v113
	v_and_b32_e32 v73, 0xffff0000, v113
	v_mul_f32_e32 v65, v65, v77
	v_mul_f32_e32 v69, v69, v73
	v_cvt_pk_bf16_f32 v65, v65, v69
	global_store_dword v[98:99], v65, off offset:256 nt
	v_fmamk_f32 v82, v74, 0x3c000000, v14
	v_mul_f32_e32 v78, 0x4b800000, v82
	v_cmp_gt_f32_e32 vcc, s14, v82
	s_nop 1
	v_cndmask_b32_e32 v82, v82, v78, vcc
	v_rsq_f32_e32 v82, v82
	s_nop 0
	v_mul_f32_e32 v78, 0x45800000, v82
	v_cndmask_b32_e32 v82, v82, v78, vcc
	v_mul_f32_e32 v66, v66, v82
	v_mul_f32_e32 v70, v70, v82
	v_mul_f32_e32 v66, v2, v66
	v_mul_f32_e32 v70, v3, v70
	v_lshlrev_b32_e32 v78, 16, v114
	v_and_b32_e32 v74, 0xffff0000, v114
	v_mul_f32_e32 v66, v66, v78
	v_mul_f32_e32 v70, v70, v74
	v_cvt_pk_bf16_f32 v66, v66, v70
	global_store_dword v[98:99], v66, off offset:512 nt
	v_fmamk_f32 v83, v75, 0x3c000000, v14
	v_mul_f32_e32 v79, 0x4b800000, v83
	v_cmp_gt_f32_e32 vcc, s14, v83
	s_nop 1
	v_cndmask_b32_e32 v83, v83, v79, vcc
	v_rsq_f32_e32 v83, v83
	s_nop 0
	v_mul_f32_e32 v79, 0x45800000, v83
	v_cndmask_b32_e32 v83, v83, v79, vcc
	v_mul_f32_e32 v67, v67, v83
	v_mul_f32_e32 v71, v71, v83
	v_mul_f32_e32 v67, v2, v67
	v_mul_f32_e32 v71, v3, v71
	v_lshlrev_b32_e32 v79, 16, v115
	v_and_b32_e32 v75, 0xffff0000, v115
	v_mul_f32_e32 v67, v67, v79
	v_mul_f32_e32 v71, v71, v75
	v_cvt_pk_bf16_f32 v67, v67, v71
	global_store_dword v[98:99], v67, off offset:768 nt
	v_lshl_add_u64 v[98:99], v[98:99], 0, s[16:17]
	global_load_dword v104, v[92:93], off nt
	global_load_dword v105, v[92:93], off offset:256 nt
	global_load_dword v106, v[92:93], off offset:512 nt
	global_load_dword v107, v[92:93], off offset:768 nt
	global_load_dword v108, v[94:95], off nt
	global_load_dword v109, v[94:95], off offset:256 nt
	global_load_dword v110, v[94:95], off offset:512 nt
	global_load_dword v111, v[94:95], off offset:768 nt
	global_load_dword v112, v[96:97], off nt
	global_load_dword v113, v[96:97], off offset:256 nt
	global_load_dword v114, v[96:97], off offset:512 nt
	global_load_dword v115, v[96:97], off offset:768 nt
	v_lshl_add_u64 v[92:93], v[92:93], 0, s[10:11]
	v_lshl_add_u64 v[94:95], v[94:95], 0, s[10:11]
	v_lshl_add_u64 v[96:97], v[96:97], 0, s[10:11]
	s_waitcnt vmcnt(40)
; DI unsigned cvt_pk_bf16(float lo, float hi) { unsigned r; asm("v_cvt_pk_bf16_f32 %0, %1, %2" : "=v"(r) : "v"(lo), "v"(hi)); return r; }
; DI void phase_combine(const Params& p) {
;     ...
;     for (int hh = 0; hh < 4; ++hh) { const size_t idx = ((size_t)tok * 512 + hh * 128 + lane * 2) >> 1; a[hh] = ofw[idx]; b[hh] = obw[idx]; g[hh] = GH[idx]; }
; #pragma unroll
;     for (int hh = 0; hh < 4; ++hh) {
;       const float o0 = __uint_as_float(a[hh] << 16) + __uint_as_float(b[hh] << 16), o1 = __uint_as_float(a[hh] & 0xffff0000u) + __uint_as_float(b[hh] & 0xffff0000u);
;       const float ss = wave_sum(o0 * o0 + o1 * o1);
;       const float rstd = rsqrtf(ss * (1.f / 128.f) + EPSN);
;       const float g0 = __uint_as_float(g[hh] << 16), g1 = __uint_as_float(g[hh] & 0xffff0000u);
;       *(unsigned*)(OC + (size_t)tok * 1024 + 512 + hh * 128 + lane * 2) = cvt_pk_bf16(o0 * rstd * w0 * g0, o1 * rstd * w1 * g1);
;     }
	v_lshlrev_b32_e32 v64, 16, v116
	v_lshlrev_b32_e32 v76, 16, v120
	v_and_b32_e32 v68, 0xffff0000, v116
	v_and_b32_e32 v80, 0xffff0000, v120
	v_add_f32_e32 v64, v64, v76
	v_add_f32_e32 v68, v68, v80
	v_mul_f32_e32 v72, v64, v64
	v_mul_f32_e32 v76, v68, v68
	v_add_f32_e32 v72, v72, v76
	v_lshlrev_b32_e32 v65, 16, v117
	v_lshlrev_b32_e32 v77, 16, v121
	v_and_b32_e32 v69, 0xffff0000, v117
	v_and_b32_e32 v81, 0xffff0000, v121
	v_add_f32_e32 v65, v65, v77
	v_add_f32_e32 v69, v69, v81
	v_mul_f32_e32 v73, v65, v65
	v_mul_f32_e32 v77, v69, v69
	v_add_f32_e32 v73, v73, v77
	v_lshlrev_b32_e32 v66, 16, v118
	v_lshlrev_b32_e32 v78, 16, v122
	v_and_b32_e32 v70, 0xffff0000, v118
	v_and_b32_e32 v82, 0xffff0000, v122
	v_add_f32_e32 v66, v66, v78
	v_add_f32_e32 v70, v70, v82
	v_mul_f32_e32 v74, v66, v66
	v_mul_f32_e32 v78, v70, v70
	v_add_f32_e32 v74, v74, v78
	v_lshlrev_b32_e32 v67, 16, v119
	v_lshlrev_b32_e32 v79, 16, v123
	v_and_b32_e32 v71, 0xffff0000, v119
	v_and_b32_e32 v83, 0xffff0000, v123
	v_add_f32_e32 v67, v67, v79
	v_add_f32_e32 v71, v71, v83
	v_mul_f32_e32 v75, v67, v67
	v_mul_f32_e32 v79, v71, v71
	v_add_f32_e32 v75, v75, v79
	ds_bpermute_b32 v76, v8, v72
	ds_bpermute_b32 v77, v8, v73
	ds_bpermute_b32 v78, v8, v74
	ds_bpermute_b32 v79, v8, v75
	s_waitcnt lgkmcnt(3)
	v_add_f32_e32 v72, v72, v76
	s_waitcnt lgkmcnt(2)
	v_add_f32_e32 v73, v73, v77
	s_waitcnt lgkmcnt(1)
	v_add_f32_e32 v74, v74, v78
	s_waitcnt lgkmcnt(0)
	v_add_f32_e32 v75, v75, v79
	ds_bpermute_b32 v76, v9, v72
	ds_bpermute_b32 v77, v9, v73
	ds_bpermute_b32 v78, v9, v74
	ds_bpermute_b32 v79, v9, v75
	s_waitcnt lgkmcnt(3)
	v_add_f32_e32 v72, v72, v76
	s_waitcnt lgkmcnt(2)
	v_add_f32_e32 v73, v73, v77
	s_waitcnt lgkmcnt(1)
	v_add_f32_e32 v74, v74, v78
	s_waitcnt lgkmcnt(0)
	v_add_f32_e32 v75, v75, v79
	ds_bpermute_b32 v76, v10, v72
	ds_bpermute_b32 v77, v10, v73
	ds_bpermute_b32 v78, v10, v74
	ds_bpermute_b32 v79, v10, v75
	s_waitcnt lgkmcnt(3)
	v_add_f32_e32 v72, v72, v76
	s_waitcnt lgkmcnt(2)
	v_add_f32_e32 v73, v73, v77
	s_waitcnt lgkmcnt(1)
	v_add_f32_e32 v74, v74, v78
	s_waitcnt lgkmcnt(0)
	v_add_f32_e32 v75, v75, v79
	ds_bpermute_b32 v76, v11, v72
	ds_bpermute_b32 v77, v11, v73
	ds_bpermute_b32 v78, v11, v74
	ds_bpermute_b32 v79, v11, v75
	s_waitcnt lgkmcnt(3)
	v_add_f32_e32 v72, v72, v76
	s_waitcnt lgkmcnt(2)
	v_add_f32_e32 v73, v73, v77
	s_waitcnt lgkmcnt(1)
	v_add_f32_e32 v74, v74, v78
	s_waitcnt lgkmcnt(0)
	v_add_f32_e32 v75, v75, v79
	ds_bpermute_b32 v76, v12, v72
	ds_bpermute_b32 v77, v12, v73
	ds_bpermute_b32 v78, v12, v74
	ds_bpermute_b32 v79, v12, v75
	s_waitcnt lgkmcnt(3)
	v_add_f32_e32 v72, v72, v76
	s_waitcnt lgkmcnt(2)
	v_add_f32_e32 v73, v73, v77
	s_waitcnt lgkmcnt(1)
	v_add_f32_e32 v74, v74, v78
	s_waitcnt lgkmcnt(0)
	v_add_f32_e32 v75, v75, v79
	ds_bpermute_b32 v76, v13, v72
	ds_bpermute_b32 v77, v13, v73
	ds_bpermute_b32 v78, v13, v74
	ds_bpermute_b32 v79, v13, v75
	s_waitcnt lgkmcnt(3)
	v_add_f32_e32 v72, v72, v76
	s_waitcnt lgkmcnt(2)
	v_add_f32_e32 v73, v73, v77
	s_waitcnt lgkmcnt(1)
	v_add_f32_e32 v74, v74, v78
	s_waitcnt lgkmcnt(0)
	v_add_f32_e32 v75, v75, v79
	v_fmamk_f32 v80, v72, 0x3c000000, v14
	v_mul_f32_e32 v76, 0x4b800000, v80
	v_cmp_gt_f32_e32 vcc, s14, v80
	s_nop 1
	v_cndmask_b32_e32 v80, v80, v76, vcc
	v_rsq_f32_e32 v80, v80
	s_nop 0
	v_mul_f32_e32 v76, 0x45800000, v80
	v_cndmask_b32_e32 v80, v80, v76, vcc
	v_mul_f32_e32 v64, v64, v80
	v_mul_f32_e32 v68, v68, v80
	v_mul_f32_e32 v64, v2, v64
	v_mul_f32_e32 v68, v3, v68
	v_lshlrev_b32_e32 v76, 16, v124
	v_and_b32_e32 v72, 0xffff0000, v124
	v_mul_f32_e32 v64, v64, v76
	v_mul_f32_e32 v68, v68, v72
	v_cvt_pk_bf16_f32 v64, v64, v68
	global_store_dword v[98:99], v64, off nt
	v_fmamk_f32 v81, v73, 0x3c000000, v14
	v_mul_f32_e32 v77, 0x4b800000, v81
	v_cmp_gt_f32_e32 vcc, s14, v81
	s_nop 1
	v_cndmask_b32_e32 v81, v81, v77, vcc
	v_rsq_f32_e32 v81, v81
	s_nop 0
	v_mul_f32_e32 v77, 0x45800000, v81
	v_cndmask_b32_e32 v81, v81, v77, vcc
	v_mul_f32_e32 v65, v65, v81
	v_mul_f32_e32 v69, v69, v81
	v_mul_f32_e32 v65, v2, v65
	v_mul_f32_e32 v69, v3, v69
	v_lshlrev_b32_e32 v77, 16, v125
	v_and_b32_e32 v73, 0xffff0000, v125
	v_mul_f32_e32 v65, v65, v77
	v_mul_f32_e32 v69, v69, v73
	v_cvt_pk_bf16_f32 v65, v65, v69
	global_store_dword v[98:99], v65, off offset:256 nt
	v_fmamk_f32 v82, v74, 0x3c000000, v14
	v_mul_f32_e32 v78, 0x4b800000, v82
	v_cmp_gt_f32_e32 vcc, s14, v82
	s_nop 1
	v_cndmask_b32_e32 v82, v82, v78, vcc
	v_rsq_f32_e32 v82, v82
	s_nop 0
	v_mul_f32_e32 v78, 0x45800000, v82
	v_cndmask_b32_e32 v82, v82, v78, vcc
	v_mul_f32_e32 v66, v66, v82
	v_mul_f32_e32 v70, v70, v82
	v_mul_f32_e32 v66, v2, v66
	v_mul_f32_e32 v70, v3, v70
	v_lshlrev_b32_e32 v78, 16, v126
	v_and_b32_e32 v74, 0xffff0000, v126
	v_mul_f32_e32 v66, v66, v78
	v_mul_f32_e32 v70, v70, v74
	v_cvt_pk_bf16_f32 v66, v66, v70
	global_store_dword v[98:99], v66, off offset:512 nt
	v_fmamk_f32 v83, v75, 0x3c000000, v14
	v_mul_f32_e32 v79, 0x4b800000, v83
	v_cmp_gt_f32_e32 vcc, s14, v83
	s_nop 1
	v_cndmask_b32_e32 v83, v83, v79, vcc
	v_rsq_f32_e32 v83, v83
	s_nop 0
	v_mul_f32_e32 v79, 0x45800000, v83
	v_cndmask_b32_e32 v83, v83, v79, vcc
	v_mul_f32_e32 v67, v67, v83
	v_mul_f32_e32 v71, v71, v83
	v_mul_f32_e32 v67, v2, v67
	v_mul_f32_e32 v71, v3, v71
	v_lshlrev_b32_e32 v79, 16, v127
	v_and_b32_e32 v75, 0xffff0000, v127
	v_mul_f32_e32 v67, v67, v79
	v_mul_f32_e32 v71, v71, v75
	v_cvt_pk_bf16_f32 v67, v67, v71
	global_store_dword v[98:99], v67, off offset:768 nt
	v_lshl_add_u64 v[98:99], v[98:99], 0, s[16:17]
	global_load_dword v116, v[92:93], off nt
	global_load_dword v117, v[92:93], off offset:256 nt
	global_load_dword v118, v[92:93], off offset:512 nt
	global_load_dword v119, v[92:93], off offset:768 nt
	global_load_dword v120, v[94:95], off nt
	global_load_dword v121, v[94:95], off offset:256 nt
	global_load_dword v122, v[94:95], off offset:512 nt
	global_load_dword v123, v[94:95], off offset:768 nt
	global_load_dword v124, v[96:97], off nt
	global_load_dword v125, v[96:97], off offset:256 nt
	global_load_dword v126, v[96:97], off offset:512 nt
	global_load_dword v127, v[96:97], off offset:768 nt
	v_lshl_add_u64 v[92:93], v[92:93], 0, s[10:11]
	v_lshl_add_u64 v[94:95], v[94:95], 0, s[10:11]
	v_lshl_add_u64 v[96:97], v[96:97], 0, s[10:11]
	s_waitcnt vmcnt(44)
; DI unsigned cvt_pk_bf16(float lo, float hi) { unsigned r; asm("v_cvt_pk_bf16_f32 %0, %1, %2" : "=v"(r) : "v"(lo), "v"(hi)); return r; }
; DI void phase_combine(const Params& p) {
;     ...
;     for (int hh = 0; hh < 4; ++hh) { const size_t idx = ((size_t)tok * 512 + hh * 128 + lane * 2) >> 1; a[hh] = ofw[idx]; b[hh] = obw[idx]; g[hh] = GH[idx]; }
; #pragma unroll
;     for (int hh = 0; hh < 4; ++hh) {
;       const float o0 = __uint_as_float(a[hh] << 16) + __uint_as_float(b[hh] << 16), o1 = __uint_as_float(a[hh] & 0xffff0000u) + __uint_as_float(b[hh] & 0xffff0000u);
;       const float ss = wave_sum(o0 * o0 + o1 * o1);
;       const float rstd = rsqrtf(ss * (1.f / 128.f) + EPSN);
;       const float g0 = __uint_as_float(g[hh] << 16), g1 = __uint_as_float(g[hh] & 0xffff0000u);
;       *(unsigned*)(OC + (size_t)tok * 1024 + 512 + hh * 128 + lane * 2) = cvt_pk_bf16(o0 * rstd * w0 * g0, o1 * rstd * w1 * g1);
;     }
	v_lshlrev_b32_e32 v64, 16, v128
	v_lshlrev_b32_e32 v76, 16, v132
	v_and_b32_e32 v68, 0xffff0000, v128
	v_and_b32_e32 v80, 0xffff0000, v132
	v_add_f32_e32 v64, v64, v76
	v_add_f32_e32 v68, v68, v80
	v_mul_f32_e32 v72, v64, v64
	v_mul_f32_e32 v76, v68, v68
	v_add_f32_e32 v72, v72, v76
	v_lshlrev_b32_e32 v65, 16, v129
	v_lshlrev_b32_e32 v77, 16, v133
	v_and_b32_e32 v69, 0xffff0000, v129
	v_and_b32_e32 v81, 0xffff0000, v133
	v_add_f32_e32 v65, v65, v77
	v_add_f32_e32 v69, v69, v81
	v_mul_f32_e32 v73, v65, v65
	v_mul_f32_e32 v77, v69, v69
	v_add_f32_e32 v73, v73, v77
	v_lshlrev_b32_e32 v66, 16, v130
	v_lshlrev_b32_e32 v78, 16, v134
	v_and_b32_e32 v70, 0xffff0000, v130
	v_and_b32_e32 v82, 0xffff0000, v134
	v_add_f32_e32 v66, v66, v78
	v_add_f32_e32 v70, v70, v82
	v_mul_f32_e32 v74, v66, v66
	v_mul_f32_e32 v78, v70, v70
	v_add_f32_e32 v74, v74, v78
	v_lshlrev_b32_e32 v67, 16, v131
	v_lshlrev_b32_e32 v79, 16, v135
	v_and_b32_e32 v71, 0xffff0000, v131
	v_and_b32_e32 v83, 0xffff0000, v135
	v_add_f32_e32 v67, v67, v79
	v_add_f32_e32 v71, v71, v83
	v_mul_f32_e32 v75, v67, v67
	v_mul_f32_e32 v79, v71, v71
	v_add_f32_e32 v75, v75, v79
	ds_bpermute_b32 v76, v8, v72
	ds_bpermute_b32 v77, v8, v73
	ds_bpermute_b32 v78, v8, v74
	ds_bpermute_b32 v79, v8, v75
	s_waitcnt lgkmcnt(3)
	v_add_f32_e32 v72, v72, v76
	s_waitcnt lgkmcnt(2)
	v_add_f32_e32 v73, v73, v77
	s_waitcnt lgkmcnt(1)
	v_add_f32_e32 v74, v74, v78
	s_waitcnt lgkmcnt(0)
	v_add_f32_e32 v75, v75, v79
	ds_bpermute_b32 v76, v9, v72
	ds_bpermute_b32 v77, v9, v73
	ds_bpermute_b32 v78, v9, v74
	ds_bpermute_b32 v79, v9, v75
	s_waitcnt lgkmcnt(3)
	v_add_f32_e32 v72, v72, v76
	s_waitcnt lgkmcnt(2)
	v_add_f32_e32 v73, v73, v77
	s_waitcnt lgkmcnt(1)
	v_add_f32_e32 v74, v74, v78
	s_waitcnt lgkmcnt(0)
	v_add_f32_e32 v75, v75, v79
	ds_bpermute_b32 v76, v10, v72
	ds_bpermute_b32 v77, v10, v73
	ds_bpermute_b32 v78, v10, v74
	ds_bpermute_b32 v79, v10, v75
	s_waitcnt lgkmcnt(3)
	v_add_f32_e32 v72, v72, v76
	s_waitcnt lgkmcnt(2)
	v_add_f32_e32 v73, v73, v77
	s_waitcnt lgkmcnt(1)
	v_add_f32_e32 v74, v74, v78
	s_waitcnt lgkmcnt(0)
	v_add_f32_e32 v75, v75, v79
	ds_bpermute_b32 v76, v11, v72
	ds_bpermute_b32 v77, v11, v73
	ds_bpermute_b32 v78, v11, v74
	ds_bpermute_b32 v79, v11, v75
	s_waitcnt lgkmcnt(3)
	v_add_f32_e32 v72, v72, v76
	s_waitcnt lgkmcnt(2)
	v_add_f32_e32 v73, v73, v77
	s_waitcnt lgkmcnt(1)
	v_add_f32_e32 v74, v74, v78
	s_waitcnt lgkmcnt(0)
	v_add_f32_e32 v75, v75, v79
	ds_bpermute_b32 v76, v12, v72
	ds_bpermute_b32 v77, v12, v73
	ds_bpermute_b32 v78, v12, v74
	ds_bpermute_b32 v79, v12, v75
	s_waitcnt lgkmcnt(3)
	v_add_f32_e32 v72, v72, v76
	s_waitcnt lgkmcnt(2)
	v_add_f32_e32 v73, v73, v77
	s_waitcnt lgkmcnt(1)
	v_add_f32_e32 v74, v74, v78
	s_waitcnt lgkmcnt(0)
	v_add_f32_e32 v75, v75, v79
	ds_bpermute_b32 v76, v13, v72
	ds_bpermute_b32 v77, v13, v73
	ds_bpermute_b32 v78, v13, v74
	ds_bpermute_b32 v79, v13, v75
	s_waitcnt lgkmcnt(3)
	v_add_f32_e32 v72, v72, v76
	s_waitcnt lgkmcnt(2)
	v_add_f32_e32 v73, v73, v77
	s_waitcnt lgkmcnt(1)
	v_add_f32_e32 v74, v74, v78
	s_waitcnt lgkmcnt(0)
	v_add_f32_e32 v75, v75, v79
	v_fmamk_f32 v80, v72, 0x3c000000, v14
	v_mul_f32_e32 v76, 0x4b800000, v80
	v_cmp_gt_f32_e32 vcc, s14, v80
	s_nop 1
	v_cndmask_b32_e32 v80, v80, v76, vcc
	v_rsq_f32_e32 v80, v80
	s_nop 0
	v_mul_f32_e32 v76, 0x45800000, v80
	v_cndmask_b32_e32 v80, v80, v76, vcc
	v_mul_f32_e32 v64, v64, v80
	v_mul_f32_e32 v68, v68, v80
	v_mul_f32_e32 v64, v2, v64
	v_mul_f32_e32 v68, v3, v68
	v_lshlrev_b32_e32 v76, 16, v136
	v_and_b32_e32 v72, 0xffff0000, v136
	v_mul_f32_e32 v64, v64, v76
	v_mul_f32_e32 v68, v68, v72
	v_cvt_pk_bf16_f32 v64, v64, v68
	global_store_dword v[98:99], v64, off nt
	v_fmamk_f32 v81, v73, 0x3c000000, v14
	v_mul_f32_e32 v77, 0x4b800000, v81
	v_cmp_gt_f32_e32 vcc, s14, v81
	s_nop 1
	v_cndmask_b32_e32 v81, v81, v77, vcc
	v_rsq_f32_e32 v81, v81
	s_nop 0
	v_mul_f32_e32 v77, 0x45800000, v81
	v_cndmask_b32_e32 v81, v81, v77, vcc
	v_mul_f32_e32 v65, v65, v81
	v_mul_f32_e32 v69, v69, v81
	v_mul_f32_e32 v65, v2, v65
	v_mul_f32_e32 v69, v3, v69
	v_lshlrev_b32_e32 v77, 16, v137
	v_and_b32_e32 v73, 0xffff0000, v137
	v_mul_f32_e32 v65, v65, v77
	v_mul_f32_e32 v69, v69, v73
	v_cvt_pk_bf16_f32 v65, v65, v69
	global_store_dword v[98:99], v65, off offset:256 nt
	v_fmamk_f32 v82, v74, 0x3c000000, v14
	v_mul_f32_e32 v78, 0x4b800000, v82
	v_cmp_gt_f32_e32 vcc, s14, v82
	s_nop 1
	v_cndmask_b32_e32 v82, v82, v78, vcc
	v_rsq_f32_e32 v82, v82
	s_nop 0
	v_mul_f32_e32 v78, 0x45800000, v82
	v_cndmask_b32_e32 v82, v82, v78, vcc
	v_mul_f32_e32 v66, v66, v82
	v_mul_f32_e32 v70, v70, v82
	v_mul_f32_e32 v66, v2, v66
	v_mul_f32_e32 v70, v3, v70
	v_lshlrev_b32_e32 v78, 16, v138
	v_and_b32_e32 v74, 0xffff0000, v138
	v_mul_f32_e32 v66, v66, v78
	v_mul_f32_e32 v70, v70, v74
	v_cvt_pk_bf16_f32 v66, v66, v70
	global_store_dword v[98:99], v66, off offset:512 nt
	v_fmamk_f32 v83, v75, 0x3c000000, v14
	v_mul_f32_e32 v79, 0x4b800000, v83
	v_cmp_gt_f32_e32 vcc, s14, v83
	s_nop 1
	v_cndmask_b32_e32 v83, v83, v79, vcc
	v_rsq_f32_e32 v83, v83
	s_nop 0
	v_mul_f32_e32 v79, 0x45800000, v83
	v_cndmask_b32_e32 v83, v83, v79, vcc
	v_mul_f32_e32 v67, v67, v83
	v_mul_f32_e32 v71, v71, v83
	v_mul_f32_e32 v67, v2, v67
	v_mul_f32_e32 v71, v3, v71
	v_lshlrev_b32_e32 v79, 16, v139
	v_and_b32_e32 v75, 0xffff0000, v139
	v_mul_f32_e32 v67, v67, v79
	v_mul_f32_e32 v71, v71, v75
	v_cvt_pk_bf16_f32 v67, v67, v71
	global_store_dword v[98:99], v67, off offset:768 nt
	v_lshl_add_u64 v[98:99], v[98:99], 0, s[16:17]
	global_load_dword v128, v[92:93], off nt
	global_load_dword v129, v[92:93], off offset:256 nt
	global_load_dword v130, v[92:93], off offset:512 nt
	global_load_dword v131, v[92:93], off offset:768 nt
	global_load_dword v132, v[94:95], off nt
	global_load_dword v133, v[94:95], off offset:256 nt
	global_load_dword v134, v[94:95], off offset:512 nt
	global_load_dword v135, v[94:95], off offset:768 nt
	global_load_dword v136, v[96:97], off nt
	global_load_dword v137, v[96:97], off offset:256 nt
	global_load_dword v138, v[96:97], off offset:512 nt
	global_load_dword v139, v[96:97], off offset:768 nt
	v_lshl_add_u64 v[92:93], v[92:93], 0, s[10:11]
	v_lshl_add_u64 v[94:95], v[94:95], 0, s[10:11]
	v_lshl_add_u64 v[96:97], v[96:97], 0, s[10:11]
	s_waitcnt vmcnt(48)
; DI unsigned cvt_pk_bf16(float lo, float hi) { unsigned r; asm("v_cvt_pk_bf16_f32 %0, %1, %2" : "=v"(r) : "v"(lo), "v"(hi)); return r; }
; DI void phase_combine(const Params& p) {
;     ...
;   for (int tok = blockIdx.x * 8 + wave; tok < NTOK; tok += gridDim.x * 8) {
;     unsigned a[4], b[4], g[4];
; #pragma unroll
;     for (int hh = 0; hh < 4; ++hh) { const size_t idx = ((size_t)tok * 512 + hh * 128 + lane * 2) >> 1; a[hh] = ofw[idx]; b[hh] = obw[idx]; g[hh] = GH[idx]; }
; #pragma unroll
;     for (int hh = 0; hh < 4; ++hh) {
;       const float o0 = __uint_as_float(a[hh] << 16) + __uint_as_float(b[hh] << 16), o1 = __uint_as_float(a[hh] & 0xffff0000u) + __uint_as_float(b[hh] & 0xffff0000u);
;       const float ss = wave_sum(o0 * o0 + o1 * o1);
;       const float rstd = rsqrtf(ss * (1.f / 128.f) + EPSN);
;       const float g0 = __uint_as_float(g[hh] << 16), g1 = __uint_as_float(g[hh] & 0xffff0000u);
;       *(unsigned*)(OC + (size_t)tok * 1024 + 512 + hh * 128 + lane * 2) = cvt_pk_bf16(o0 * rstd * w0 * g0, o1 * rstd * w1 * g1);
;     }
	v_lshlrev_b32_e32 v64, 16, v140
	v_lshlrev_b32_e32 v76, 16, v144
	v_and_b32_e32 v68, 0xffff0000, v140
	v_and_b32_e32 v80, 0xffff0000, v144
	v_add_f32_e32 v64, v64, v76
	v_add_f32_e32 v68, v68, v80
	v_mul_f32_e32 v72, v64, v64
	v_mul_f32_e32 v76, v68, v68
	v_add_f32_e32 v72, v72, v76
	v_lshlrev_b32_e32 v65, 16, v141
	v_lshlrev_b32_e32 v77, 16, v145
	v_and_b32_e32 v69, 0xffff0000, v141
	v_and_b32_e32 v81, 0xffff0000, v145
	v_add_f32_e32 v65, v65, v77
	v_add_f32_e32 v69, v69, v81
	v_mul_f32_e32 v73, v65, v65
	v_mul_f32_e32 v77, v69, v69
	v_add_f32_e32 v73, v73, v77
	v_lshlrev_b32_e32 v66, 16, v142
	v_lshlrev_b32_e32 v78, 16, v146
	v_and_b32_e32 v70, 0xffff0000, v142
	v_and_b32_e32 v82, 0xffff0000, v146
	v_add_f32_e32 v66, v66, v78
	v_add_f32_e32 v70, v70, v82
	v_mul_f32_e32 v74, v66, v66
	v_mul_f32_e32 v78, v70, v70
	v_add_f32_e32 v74, v74, v78
	v_lshlrev_b32_e32 v67, 16, v143
	v_lshlrev_b32_e32 v79, 16, v147
	v_and_b32_e32 v71, 0xffff0000, v143
	v_and_b32_e32 v83, 0xffff0000, v147
	v_add_f32_e32 v67, v67, v79
	v_add_f32_e32 v71, v71, v83
	v_mul_f32_e32 v75, v67, v67
	v_mul_f32_e32 v79, v71, v71
	v_add_f32_e32 v75, v75, v79
	ds_bpermute_b32 v76, v8, v72
	ds_bpermute_b32 v77, v8, v73
	ds_bpermute_b32 v78, v8, v74
	ds_bpermute_b32 v79, v8, v75
	s_waitcnt lgkmcnt(3)
	v_add_f32_e32 v72, v72, v76
	s_waitcnt lgkmcnt(2)
	v_add_f32_e32 v73, v73, v77
	s_waitcnt lgkmcnt(1)
	v_add_f32_e32 v74, v74, v78
	s_waitcnt lgkmcnt(0)
	v_add_f32_e32 v75, v75, v79
	ds_bpermute_b32 v76, v9, v72
	ds_bpermute_b32 v77, v9, v73
	ds_bpermute_b32 v78, v9, v74
	ds_bpermute_b32 v79, v9, v75
	s_waitcnt lgkmcnt(3)
	v_add_f32_e32 v72, v72, v76
	s_waitcnt lgkmcnt(2)
	v_add_f32_e32 v73, v73, v77
	s_waitcnt lgkmcnt(1)
	v_add_f32_e32 v74, v74, v78
	s_waitcnt lgkmcnt(0)
	v_add_f32_e32 v75, v75, v79
	ds_bpermute_b32 v76, v10, v72
	ds_bpermute_b32 v77, v10, v73
	ds_bpermute_b32 v78, v10, v74
	ds_bpermute_b32 v79, v10, v75
	s_waitcnt lgkmcnt(3)
	v_add_f32_e32 v72, v72, v76
	s_waitcnt lgkmcnt(2)
	v_add_f32_e32 v73, v73, v77
	s_waitcnt lgkmcnt(1)
	v_add_f32_e32 v74, v74, v78
	s_waitcnt lgkmcnt(0)
	v_add_f32_e32 v75, v75, v79
	ds_bpermute_b32 v76, v11, v72
	ds_bpermute_b32 v77, v11, v73
	ds_bpermute_b32 v78, v11, v74
	ds_bpermute_b32 v79, v11, v75
	s_waitcnt lgkmcnt(3)
	v_add_f32_e32 v72, v72, v76
	s_waitcnt lgkmcnt(2)
	v_add_f32_e32 v73, v73, v77
	s_waitcnt lgkmcnt(1)
	v_add_f32_e32 v74, v74, v78
	s_waitcnt lgkmcnt(0)
	v_add_f32_e32 v75, v75, v79
	ds_bpermute_b32 v76, v12, v72
	ds_bpermute_b32 v77, v12, v73
	ds_bpermute_b32 v78, v12, v74
	ds_bpermute_b32 v79, v12, v75
	s_waitcnt lgkmcnt(3)
	v_add_f32_e32 v72, v72, v76
	s_waitcnt lgkmcnt(2)
	v_add_f32_e32 v73, v73, v77
	s_waitcnt lgkmcnt(1)
	v_add_f32_e32 v74, v74, v78
	s_waitcnt lgkmcnt(0)
	v_add_f32_e32 v75, v75, v79
	ds_bpermute_b32 v76, v13, v72
	ds_bpermute_b32 v77, v13, v73
	ds_bpermute_b32 v78, v13, v74
	ds_bpermute_b32 v79, v13, v75
	s_waitcnt lgkmcnt(3)
	v_add_f32_e32 v72, v72, v76
	s_waitcnt lgkmcnt(2)
	v_add_f32_e32 v73, v73, v77
	s_waitcnt lgkmcnt(1)
	v_add_f32_e32 v74, v74, v78
	s_waitcnt lgkmcnt(0)
	v_add_f32_e32 v75, v75, v79
	v_fmamk_f32 v80, v72, 0x3c000000, v14
	v_mul_f32_e32 v76, 0x4b800000, v80
	v_cmp_gt_f32_e32 vcc, s14, v80
	s_nop 1
	v_cndmask_b32_e32 v80, v80, v76, vcc
	v_rsq_f32_e32 v80, v80
	s_nop 0
	v_mul_f32_e32 v76, 0x45800000, v80
	v_cndmask_b32_e32 v80, v80, v76, vcc
	v_mul_f32_e32 v64, v64, v80
	v_mul_f32_e32 v68, v68, v80
	v_mul_f32_e32 v64, v2, v64
	v_mul_f32_e32 v68, v3, v68
	v_lshlrev_b32_e32 v76, 16, v148
	v_and_b32_e32 v72, 0xffff0000, v148
	v_mul_f32_e32 v64, v64, v76
	v_mul_f32_e32 v68, v68, v72
	v_cvt_pk_bf16_f32 v64, v64, v68
	global_store_dword v[98:99], v64, off nt
	v_fmamk_f32 v81, v73, 0x3c000000, v14
	v_mul_f32_e32 v77, 0x4b800000, v81
	v_cmp_gt_f32_e32 vcc, s14, v81
	s_nop 1
	v_cndmask_b32_e32 v81, v81, v77, vcc
	v_rsq_f32_e32 v81, v81
	s_nop 0
	v_mul_f32_e32 v77, 0x45800000, v81
	v_cndmask_b32_e32 v81, v81, v77, vcc
	v_mul_f32_e32 v65, v65, v81
	v_mul_f32_e32 v69, v69, v81
	v_mul_f32_e32 v65, v2, v65
	v_mul_f32_e32 v69, v3, v69
	v_lshlrev_b32_e32 v77, 16, v149
	v_and_b32_e32 v73, 0xffff0000, v149
	v_mul_f32_e32 v65, v65, v77
	v_mul_f32_e32 v69, v69, v73
	v_cvt_pk_bf16_f32 v65, v65, v69
	global_store_dword v[98:99], v65, off offset:256 nt
	v_fmamk_f32 v82, v74, 0x3c000000, v14
	v_mul_f32_e32 v78, 0x4b800000, v82
	v_cmp_gt_f32_e32 vcc, s14, v82
	s_nop 1
	v_cndmask_b32_e32 v82, v82, v78, vcc
	v_rsq_f32_e32 v82, v82
	s_nop 0
	v_mul_f32_e32 v78, 0x45800000, v82
	v_cndmask_b32_e32 v82, v82, v78, vcc
	v_mul_f32_e32 v66, v66, v82
	v_mul_f32_e32 v70, v70, v82
	v_mul_f32_e32 v66, v2, v66
	v_mul_f32_e32 v70, v3, v70
	v_lshlrev_b32_e32 v78, 16, v150
	v_and_b32_e32 v74, 0xffff0000, v150
	v_mul_f32_e32 v66, v66, v78
	v_mul_f32_e32 v70, v70, v74
	v_cvt_pk_bf16_f32 v66, v66, v70
	global_store_dword v[98:99], v66, off offset:512 nt
	v_fmamk_f32 v83, v75, 0x3c000000, v14
	v_mul_f32_e32 v79, 0x4b800000, v83
	v_cmp_gt_f32_e32 vcc, s14, v83
	s_nop 1
	v_cndmask_b32_e32 v83, v83, v79, vcc
	v_rsq_f32_e32 v83, v83
	s_nop 0
	v_mul_f32_e32 v79, 0x45800000, v83
	v_cndmask_b32_e32 v83, v83, v79, vcc
	v_mul_f32_e32 v67, v67, v83
	v_mul_f32_e32 v71, v71, v83
	v_mul_f32_e32 v67, v2, v67
	v_mul_f32_e32 v71, v3, v71
	v_lshlrev_b32_e32 v79, 16, v151
	v_and_b32_e32 v75, 0xffff0000, v151
	v_mul_f32_e32 v67, v67, v79
	v_mul_f32_e32 v71, v71, v75
	v_cvt_pk_bf16_f32 v67, v67, v71
	global_store_dword v[98:99], v67, off offset:768 nt
	v_lshl_add_u64 v[98:99], v[98:99], 0, s[16:17]
	global_load_dword v140, v[92:93], off nt
	global_load_dword v141, v[92:93], off offset:256 nt
	global_load_dword v142, v[92:93], off offset:512 nt
	global_load_dword v143, v[92:93], off offset:768 nt
	global_load_dword v144, v[94:95], off nt
	global_load_dword v145, v[94:95], off offset:256 nt
	global_load_dword v146, v[94:95], off offset:512 nt
	global_load_dword v147, v[94:95], off offset:768 nt
	global_load_dword v148, v[96:97], off nt
	global_load_dword v149, v[96:97], off offset:256 nt
	global_load_dword v150, v[96:97], off offset:512 nt
	global_load_dword v151, v[96:97], off offset:768 nt
	v_lshl_add_u64 v[92:93], v[92:93], 0, s[10:11]
	v_lshl_add_u64 v[94:95], v[94:95], 0, s[10:11]
	v_lshl_add_u64 v[96:97], v[96:97], 0, s[10:11]
	s_sub_i32 s98, s98, 1
	s_cmp_lg_u32 s98, 0
	s_cbranch_scc1 .Lcq_loop
; DI unsigned cvt_pk_bf16(float lo, float hi) { unsigned r; asm("v_cvt_pk_bf16_f32 %0, %1, %2" : "=v"(r) : "v"(lo), "v"(hi)); return r; }
; DI void phase_combine(const Params& p) {
;     ...
;     for (int hh = 0; hh < 4; ++hh) { const size_t idx = ((size_t)tok * 512 + hh * 128 + lane * 2) >> 1; a[hh] = ofw[idx]; b[hh] = obw[idx]; g[hh] = GH[idx]; }
; #pragma unroll
;     for (int hh = 0; hh < 4; ++hh) {
;       const float o0 = __uint_as_float(a[hh] << 16) + __uint_as_float(b[hh] << 16), o1 = __uint_as_float(a[hh] & 0xffff0000u) + __uint_as_float(b[hh] & 0xffff0000u);
;       const float ss = wave_sum(o0 * o0 + o1 * o1);
;       const float rstd = rsqrtf(ss * (1.f / 128.f) + EPSN);
;       const float g0 = __uint_as_float(g[hh] << 16), g1 = __uint_as_float(g[hh] & 0xffff0000u);
;       *(unsigned*)(OC + (size_t)tok * 1024 + 512 + hh * 128 + lane * 2) = cvt_pk_bf16(o0 * rstd * w0 * g0, o1 * rstd * w1 * g1);
;     }
	s_waitcnt vmcnt(48)
	v_lshlrev_b32_e32 v64, 16, v104
	v_lshlrev_b32_e32 v76, 16, v108
	v_and_b32_e32 v68, 0xffff0000, v104
	v_and_b32_e32 v80, 0xffff0000, v108
	v_add_f32_e32 v64, v64, v76
	v_add_f32_e32 v68, v68, v80
	v_mul_f32_e32 v72, v64, v64
	v_mul_f32_e32 v76, v68, v68
	v_add_f32_e32 v72, v72, v76
	v_lshlrev_b32_e32 v65, 16, v105
	v_lshlrev_b32_e32 v77, 16, v109
	v_and_b32_e32 v69, 0xffff0000, v105
	v_and_b32_e32 v81, 0xffff0000, v109
	v_add_f32_e32 v65, v65, v77
	v_add_f32_e32 v69, v69, v81
	v_mul_f32_e32 v73, v65, v65
	v_mul_f32_e32 v77, v69, v69
	v_add_f32_e32 v73, v73, v77
	v_lshlrev_b32_e32 v66, 16, v106
	v_lshlrev_b32_e32 v78, 16, v110
	v_and_b32_e32 v70, 0xffff0000, v106
	v_and_b32_e32 v82, 0xffff0000, v110
	v_add_f32_e32 v66, v66, v78
	v_add_f32_e32 v70, v70, v82
	v_mul_f32_e32 v74, v66, v66
	v_mul_f32_e32 v78, v70, v70
	v_add_f32_e32 v74, v74, v78
	v_lshlrev_b32_e32 v67, 16, v107
	v_lshlrev_b32_e32 v79, 16, v111
	v_and_b32_e32 v71, 0xffff0000, v107
	v_and_b32_e32 v83, 0xffff0000, v111
	v_add_f32_e32 v67, v67, v79
	v_add_f32_e32 v71, v71, v83
	v_mul_f32_e32 v75, v67, v67
	v_mul_f32_e32 v79, v71, v71
	v_add_f32_e32 v75, v75, v79
	ds_bpermute_b32 v76, v8, v72
	ds_bpermute_b32 v77, v8, v73
	ds_bpermute_b32 v78, v8, v74
	ds_bpermute_b32 v79, v8, v75
	s_waitcnt lgkmcnt(3)
	v_add_f32_e32 v72, v72, v76
	s_waitcnt lgkmcnt(2)
	v_add_f32_e32 v73, v73, v77
	s_waitcnt lgkmcnt(1)
	v_add_f32_e32 v74, v74, v78
	s_waitcnt lgkmcnt(0)
	v_add_f32_e32 v75, v75, v79
	ds_bpermute_b32 v76, v9, v72
	ds_bpermute_b32 v77, v9, v73
	ds_bpermute_b32 v78, v9, v74
	ds_bpermute_b32 v79, v9, v75
	s_waitcnt lgkmcnt(3)
	v_add_f32_e32 v72, v72, v76
	s_waitcnt lgkmcnt(2)
	v_add_f32_e32 v73, v73, v77
	s_waitcnt lgkmcnt(1)
	v_add_f32_e32 v74, v74, v78
	s_waitcnt lgkmcnt(0)
	v_add_f32_e32 v75, v75, v79
	ds_bpermute_b32 v76, v10, v72
	ds_bpermute_b32 v77, v10, v73
	ds_bpermute_b32 v78, v10, v74
	ds_bpermute_b32 v79, v10, v75
	s_waitcnt lgkmcnt(3)
	v_add_f32_e32 v72, v72, v76
	s_waitcnt lgkmcnt(2)
	v_add_f32_e32 v73, v73, v77
	s_waitcnt lgkmcnt(1)
	v_add_f32_e32 v74, v74, v78
	s_waitcnt lgkmcnt(0)
	v_add_f32_e32 v75, v75, v79
	ds_bpermute_b32 v76, v11, v72
	ds_bpermute_b32 v77, v11, v73
	ds_bpermute_b32 v78, v11, v74
	ds_bpermute_b32 v79, v11, v75
	s_waitcnt lgkmcnt(3)
	v_add_f32_e32 v72, v72, v76
	s_waitcnt lgkmcnt(2)
	v_add_f32_e32 v73, v73, v77
	s_waitcnt lgkmcnt(1)
	v_add_f32_e32 v74, v74, v78
	s_waitcnt lgkmcnt(0)
	v_add_f32_e32 v75, v75, v79
	ds_bpermute_b32 v76, v12, v72
	ds_bpermute_b32 v77, v12, v73
	ds_bpermute_b32 v78, v12, v74
	ds_bpermute_b32 v79, v12, v75
	s_waitcnt lgkmcnt(3)
	v_add_f32_e32 v72, v72, v76
	s_waitcnt lgkmcnt(2)
	v_add_f32_e32 v73, v73, v77
	s_waitcnt lgkmcnt(1)
	v_add_f32_e32 v74, v74, v78
	s_waitcnt lgkmcnt(0)
	v_add_f32_e32 v75, v75, v79
	ds_bpermute_b32 v76, v13, v72
	ds_bpermute_b32 v77, v13, v73
	ds_bpermute_b32 v78, v13, v74
	ds_bpermute_b32 v79, v13, v75
	s_waitcnt lgkmcnt(3)
	v_add_f32_e32 v72, v72, v76
	s_waitcnt lgkmcnt(2)
	v_add_f32_e32 v73, v73, v77
	s_waitcnt lgkmcnt(1)
	v_add_f32_e32 v74, v74, v78
	s_waitcnt lgkmcnt(0)
	v_add_f32_e32 v75, v75, v79
	v_fmamk_f32 v80, v72, 0x3c000000, v14
	v_mul_f32_e32 v76, 0x4b800000, v80
	v_cmp_gt_f32_e32 vcc, s14, v80
	s_nop 1
	v_cndmask_b32_e32 v80, v80, v76, vcc
	v_rsq_f32_e32 v80, v80
	s_nop 0
	v_mul_f32_e32 v76, 0x45800000, v80
	v_cndmask_b32_e32 v80, v80, v76, vcc
	v_mul_f32_e32 v64, v64, v80
	v_mul_f32_e32 v68, v68, v80
	v_mul_f32_e32 v64, v2, v64
	v_mul_f32_e32 v68, v3, v68
	v_lshlrev_b32_e32 v76, 16, v112
	v_and_b32_e32 v72, 0xffff0000, v112
	v_mul_f32_e32 v64, v64, v76
	v_mul_f32_e32 v68, v68, v72
	v_cvt_pk_bf16_f32 v64, v64, v68
	global_store_dword v[98:99], v64, off nt
	v_fmamk_f32 v81, v73, 0x3c000000, v14
	v_mul_f32_e32 v77, 0x4b800000, v81
	v_cmp_gt_f32_e32 vcc, s14, v81
	s_nop 1
	v_cndmask_b32_e32 v81, v81, v77, vcc
	v_rsq_f32_e32 v81, v81
	s_nop 0
	v_mul_f32_e32 v77, 0x45800000, v81
	v_cndmask_b32_e32 v81, v81, v77, vcc
	v_mul_f32_e32 v65, v65, v81
	v_mul_f32_e32 v69, v69, v81
	v_mul_f32_e32 v65, v2, v65
	v_mul_f32_e32 v69, v3, v69
	v_lshlrev_b32_e32 v77, 16, v113
	v_and_b32_e32 v73, 0xffff0000, v113
	v_mul_f32_e32 v65, v65, v77
	v_mul_f32_e32 v69, v69, v73
	v_cvt_pk_bf16_f32 v65, v65, v69
	global_store_dword v[98:99], v65, off offset:256 nt
	v_fmamk_f32 v82, v74, 0x3c000000, v14
	v_mul_f32_e32 v78, 0x4b800000, v82
	v_cmp_gt_f32_e32 vcc, s14, v82
	s_nop 1
	v_cndmask_b32_e32 v82, v82, v78, vcc
	v_rsq_f32_e32 v82, v82
	s_nop 0
	v_mul_f32_e32 v78, 0x45800000, v82
	v_cndmask_b32_e32 v82, v82, v78, vcc
	v_mul_f32_e32 v66, v66, v82
	v_mul_f32_e32 v70, v70, v82
	v_mul_f32_e32 v66, v2, v66
	v_mul_f32_e32 v70, v3, v70
	v_lshlrev_b32_e32 v78, 16, v114
	v_and_b32_e32 v74, 0xffff0000, v114
	v_mul_f32_e32 v66, v66, v78
	v_mul_f32_e32 v70, v70, v74
	v_cvt_pk_bf16_f32 v66, v66, v70
	global_store_dword v[98:99], v66, off offset:512 nt
	v_fmamk_f32 v83, v75, 0x3c000000, v14
	v_mul_f32_e32 v79, 0x4b800000, v83
	v_cmp_gt_f32_e32 vcc, s14, v83
	s_nop 1
	v_cndmask_b32_e32 v83, v83, v79, vcc
	v_rsq_f32_e32 v83, v83
	s_nop 0
	v_mul_f32_e32 v79, 0x45800000, v83
	v_cndmask_b32_e32 v83, v83, v79, vcc
	v_mul_f32_e32 v67, v67, v83
	v_mul_f32_e32 v71, v71, v83
	v_mul_f32_e32 v67, v2, v67
	v_mul_f32_e32 v71, v3, v71
	v_lshlrev_b32_e32 v79, 16, v115
	v_and_b32_e32 v75, 0xffff0000, v115
	v_mul_f32_e32 v67, v67, v79
	v_mul_f32_e32 v71, v71, v75
	v_cvt_pk_bf16_f32 v67, v67, v71
	global_store_dword v[98:99], v67, off offset:768 nt
	v_lshl_add_u64 v[98:99], v[98:99], 0, s[16:17]
	s_waitcnt vmcnt(36)
; DI unsigned cvt_pk_bf16(float lo, float hi) { unsigned r; asm("v_cvt_pk_bf16_f32 %0, %1, %2" : "=v"(r) : "v"(lo), "v"(hi)); return r; }
; DI void phase_combine(const Params& p) {
;     ...
;     for (int hh = 0; hh < 4; ++hh) { const size_t idx = ((size_t)tok * 512 + hh * 128 + lane * 2) >> 1; a[hh] = ofw[idx]; b[hh] = obw[idx]; g[hh] = GH[idx]; }
; #pragma unroll
;     for (int hh = 0; hh < 4; ++hh) {
;       const float o0 = __uint_as_float(a[hh] << 16) + __uint_as_float(b[hh] << 16), o1 = __uint_as_float(a[hh] & 0xffff0000u) + __uint_as_float(b[hh] & 0xffff0000u);
;       const float ss = wave_sum(o0 * o0 + o1 * o1);
;       const float rstd = rsqrtf(ss * (1.f / 128.f) + EPSN);
;       const float g0 = __uint_as_float(g[hh] << 16), g1 = __uint_as_float(g[hh] & 0xffff0000u);
;       *(unsigned*)(OC + (size_t)tok * 1024 + 512 + hh * 128 + lane * 2) = cvt_pk_bf16(o0 * rstd * w0 * g0, o1 * rstd * w1 * g1);
;     }
	v_lshlrev_b32_e32 v64, 16, v116
	v_lshlrev_b32_e32 v76, 16, v120
	v_and_b32_e32 v68, 0xffff0000, v116
	v_and_b32_e32 v80, 0xffff0000, v120
	v_add_f32_e32 v64, v64, v76
	v_add_f32_e32 v68, v68, v80
	v_mul_f32_e32 v72, v64, v64
	v_mul_f32_e32 v76, v68, v68
	v_add_f32_e32 v72, v72, v76
	v_lshlrev_b32_e32 v65, 16, v117
	v_lshlrev_b32_e32 v77, 16, v121
	v_and_b32_e32 v69, 0xffff0000, v117
	v_and_b32_e32 v81, 0xffff0000, v121
	v_add_f32_e32 v65, v65, v77
	v_add_f32_e32 v69, v69, v81
	v_mul_f32_e32 v73, v65, v65
	v_mul_f32_e32 v77, v69, v69
	v_add_f32_e32 v73, v73, v77
	v_lshlrev_b32_e32 v66, 16, v118
	v_lshlrev_b32_e32 v78, 16, v122
	v_and_b32_e32 v70, 0xffff0000, v118
	v_and_b32_e32 v82, 0xffff0000, v122
	v_add_f32_e32 v66, v66, v78
	v_add_f32_e32 v70, v70, v82
	v_mul_f32_e32 v74, v66, v66
	v_mul_f32_e32 v78, v70, v70
	v_add_f32_e32 v74, v74, v78
	v_lshlrev_b32_e32 v67, 16, v119
	v_lshlrev_b32_e32 v79, 16, v123
	v_and_b32_e32 v71, 0xffff0000, v119
	v_and_b32_e32 v83, 0xffff0000, v123
	v_add_f32_e32 v67, v67, v79
	v_add_f32_e32 v71, v71, v83
	v_mul_f32_e32 v75, v67, v67
	v_mul_f32_e32 v79, v71, v71
	v_add_f32_e32 v75, v75, v79
	ds_bpermute_b32 v76, v8, v72
	ds_bpermute_b32 v77, v8, v73
	ds_bpermute_b32 v78, v8, v74
	ds_bpermute_b32 v79, v8, v75
	s_waitcnt lgkmcnt(3)
	v_add_f32_e32 v72, v72, v76
	s_waitcnt lgkmcnt(2)
	v_add_f32_e32 v73, v73, v77
	s_waitcnt lgkmcnt(1)
	v_add_f32_e32 v74, v74, v78
	s_waitcnt lgkmcnt(0)
	v_add_f32_e32 v75, v75, v79
	ds_bpermute_b32 v76, v9, v72
	ds_bpermute_b32 v77, v9, v73
	ds_bpermute_b32 v78, v9, v74
	ds_bpermute_b32 v79, v9, v75
	s_waitcnt lgkmcnt(3)
	v_add_f32_e32 v72, v72, v76
	s_waitcnt lgkmcnt(2)
	v_add_f32_e32 v73, v73, v77
	s_waitcnt lgkmcnt(1)
	v_add_f32_e32 v74, v74, v78
	s_waitcnt lgkmcnt(0)
	v_add_f32_e32 v75, v75, v79
	ds_bpermute_b32 v76, v10, v72
	ds_bpermute_b32 v77, v10, v73
	ds_bpermute_b32 v78, v10, v74
	ds_bpermute_b32 v79, v10, v75
	s_waitcnt lgkmcnt(3)
	v_add_f32_e32 v72, v72, v76
	s_waitcnt lgkmcnt(2)
	v_add_f32_e32 v73, v73, v77
	s_waitcnt lgkmcnt(1)
	v_add_f32_e32 v74, v74, v78
	s_waitcnt lgkmcnt(0)
	v_add_f32_e32 v75, v75, v79
	ds_bpermute_b32 v76, v11, v72
	ds_bpermute_b32 v77, v11, v73
	ds_bpermute_b32 v78, v11, v74
	ds_bpermute_b32 v79, v11, v75
	s_waitcnt lgkmcnt(3)
	v_add_f32_e32 v72, v72, v76
	s_waitcnt lgkmcnt(2)
	v_add_f32_e32 v73, v73, v77
	s_waitcnt lgkmcnt(1)
	v_add_f32_e32 v74, v74, v78
	s_waitcnt lgkmcnt(0)
	v_add_f32_e32 v75, v75, v79
	ds_bpermute_b32 v76, v12, v72
	ds_bpermute_b32 v77, v12, v73
	ds_bpermute_b32 v78, v12, v74
	ds_bpermute_b32 v79, v12, v75
	s_waitcnt lgkmcnt(3)
	v_add_f32_e32 v72, v72, v76
	s_waitcnt lgkmcnt(2)
	v_add_f32_e32 v73, v73, v77
	s_waitcnt lgkmcnt(1)
	v_add_f32_e32 v74, v74, v78
	s_waitcnt lgkmcnt(0)
	v_add_f32_e32 v75, v75, v79
	ds_bpermute_b32 v76, v13, v72
	ds_bpermute_b32 v77, v13, v73
	ds_bpermute_b32 v78, v13, v74
	ds_bpermute_b32 v79, v13, v75
	s_waitcnt lgkmcnt(3)
	v_add_f32_e32 v72, v72, v76
	s_waitcnt lgkmcnt(2)
	v_add_f32_e32 v73, v73, v77
	s_waitcnt lgkmcnt(1)
	v_add_f32_e32 v74, v74, v78
	s_waitcnt lgkmcnt(0)
	v_add_f32_e32 v75, v75, v79
	v_fmamk_f32 v80, v72, 0x3c000000, v14
	v_mul_f32_e32 v76, 0x4b800000, v80
	v_cmp_gt_f32_e32 vcc, s14, v80
	s_nop 1
	v_cndmask_b32_e32 v80, v80, v76, vcc
	v_rsq_f32_e32 v80, v80
	s_nop 0
	v_mul_f32_e32 v76, 0x45800000, v80
	v_cndmask_b32_e32 v80, v80, v76, vcc
	v_mul_f32_e32 v64, v64, v80
	v_mul_f32_e32 v68, v68, v80
	v_mul_f32_e32 v64, v2, v64
	v_mul_f32_e32 v68, v3, v68
	v_lshlrev_b32_e32 v76, 16, v124
	v_and_b32_e32 v72, 0xffff0000, v124
	v_mul_f32_e32 v64, v64, v76
	v_mul_f32_e32 v68, v68, v72
	v_cvt_pk_bf16_f32 v64, v64, v68
	global_store_dword v[98:99], v64, off nt
	v_fmamk_f32 v81, v73, 0x3c000000, v14
	v_mul_f32_e32 v77, 0x4b800000, v81
	v_cmp_gt_f32_e32 vcc, s14, v81
	s_nop 1
	v_cndmask_b32_e32 v81, v81, v77, vcc
	v_rsq_f32_e32 v81, v81
	s_nop 0
	v_mul_f32_e32 v77, 0x45800000, v81
	v_cndmask_b32_e32 v81, v81, v77, vcc
	v_mul_f32_e32 v65, v65, v81
	v_mul_f32_e32 v69, v69, v81
	v_mul_f32_e32 v65, v2, v65
	v_mul_f32_e32 v69, v3, v69
	v_lshlrev_b32_e32 v77, 16, v125
	v_and_b32_e32 v73, 0xffff0000, v125
	v_mul_f32_e32 v65, v65, v77
	v_mul_f32_e32 v69, v69, v73
	v_cvt_pk_bf16_f32 v65, v65, v69
	global_store_dword v[98:99], v65, off offset:256 nt
	v_fmamk_f32 v82, v74, 0x3c000000, v14
	v_mul_f32_e32 v78, 0x4b800000, v82
	v_cmp_gt_f32_e32 vcc, s14, v82
	s_nop 1
	v_cndmask_b32_e32 v82, v82, v78, vcc
	v_rsq_f32_e32 v82, v82
	s_nop 0
	v_mul_f32_e32 v78, 0x45800000, v82
	v_cndmask_b32_e32 v82, v82, v78, vcc
	v_mul_f32_e32 v66, v66, v82
	v_mul_f32_e32 v70, v70, v82
	v_mul_f32_e32 v66, v2, v66
	v_mul_f32_e32 v70, v3, v70
	v_lshlrev_b32_e32 v78, 16, v126
	v_and_b32_e32 v74, 0xffff0000, v126
	v_mul_f32_e32 v66, v66, v78
	v_mul_f32_e32 v70, v70, v74
	v_cvt_pk_bf16_f32 v66, v66, v70
	global_store_dword v[98:99], v66, off offset:512 nt
	v_fmamk_f32 v83, v75, 0x3c000000, v14
	v_mul_f32_e32 v79, 0x4b800000, v83
	v_cmp_gt_f32_e32 vcc, s14, v83
	s_nop 1
	v_cndmask_b32_e32 v83, v83, v79, vcc
	v_rsq_f32_e32 v83, v83
	s_nop 0
	v_mul_f32_e32 v79, 0x45800000, v83
	v_cndmask_b32_e32 v83, v83, v79, vcc
	v_mul_f32_e32 v67, v67, v83
	v_mul_f32_e32 v71, v71, v83
	v_mul_f32_e32 v67, v2, v67
	v_mul_f32_e32 v71, v3, v71
	v_lshlrev_b32_e32 v79, 16, v127
	v_and_b32_e32 v75, 0xffff0000, v127
	v_mul_f32_e32 v67, v67, v79
	v_mul_f32_e32 v71, v71, v75
	v_cvt_pk_bf16_f32 v67, v67, v71
	global_store_dword v[98:99], v67, off offset:768 nt
	v_lshl_add_u64 v[98:99], v[98:99], 0, s[16:17]
	s_waitcnt vmcnt(24)
; DI unsigned cvt_pk_bf16(float lo, float hi) { unsigned r; asm("v_cvt_pk_bf16_f32 %0, %1, %2" : "=v"(r) : "v"(lo), "v"(hi)); return r; }
; DI void phase_combine(const Params& p) {
;     ...
;     for (int hh = 0; hh < 4; ++hh) { const size_t idx = ((size_t)tok * 512 + hh * 128 + lane * 2) >> 1; a[hh] = ofw[idx]; b[hh] = obw[idx]; g[hh] = GH[idx]; }
; #pragma unroll
;     for (int hh = 0; hh < 4; ++hh) {
;       const float o0 = __uint_as_float(a[hh] << 16) + __uint_as_float(b[hh] << 16), o1 = __uint_as_float(a[hh] & 0xffff0000u) + __uint_as_float(b[hh] & 0xffff0000u);
;       const float ss = wave_sum(o0 * o0 + o1 * o1);
;       const float rstd = rsqrtf(ss * (1.f / 128.f) + EPSN);
;       const float g0 = __uint_as_float(g[hh] << 16), g1 = __uint_as_float(g[hh] & 0xffff0000u);
;       *(unsigned*)(OC + (size_t)tok * 1024 + 512 + hh * 128 + lane * 2) = cvt_pk_bf16(o0 * rstd * w0 * g0, o1 * rstd * w1 * g1);
;     }
	v_lshlrev_b32_e32 v64, 16, v128
	v_lshlrev_b32_e32 v76, 16, v132
	v_and_b32_e32 v68, 0xffff0000, v128
	v_and_b32_e32 v80, 0xffff0000, v132
	v_add_f32_e32 v64, v64, v76
	v_add_f32_e32 v68, v68, v80
	v_mul_f32_e32 v72, v64, v64
	v_mul_f32_e32 v76, v68, v68
	v_add_f32_e32 v72, v72, v76
	v_lshlrev_b32_e32 v65, 16, v129
	v_lshlrev_b32_e32 v77, 16, v133
	v_and_b32_e32 v69, 0xffff0000, v129
	v_and_b32_e32 v81, 0xffff0000, v133
	v_add_f32_e32 v65, v65, v77
	v_add_f32_e32 v69, v69, v81
	v_mul_f32_e32 v73, v65, v65
	v_mul_f32_e32 v77, v69, v69
	v_add_f32_e32 v73, v73, v77
	v_lshlrev_b32_e32 v66, 16, v130
	v_lshlrev_b32_e32 v78, 16, v134
	v_and_b32_e32 v70, 0xffff0000, v130
	v_and_b32_e32 v82, 0xffff0000, v134
	v_add_f32_e32 v66, v66, v78
	v_add_f32_e32 v70, v70, v82
	v_mul_f32_e32 v74, v66, v66
	v_mul_f32_e32 v78, v70, v70
	v_add_f32_e32 v74, v74, v78
	v_lshlrev_b32_e32 v67, 16, v131
	v_lshlrev_b32_e32 v79, 16, v135
	v_and_b32_e32 v71, 0xffff0000, v131
	v_and_b32_e32 v83, 0xffff0000, v135
	v_add_f32_e32 v67, v67, v79
	v_add_f32_e32 v71, v71, v83
	v_mul_f32_e32 v75, v67, v67
	v_mul_f32_e32 v79, v71, v71
	v_add_f32_e32 v75, v75, v79
	ds_bpermute_b32 v76, v8, v72
	ds_bpermute_b32 v77, v8, v73
	ds_bpermute_b32 v78, v8, v74
	ds_bpermute_b32 v79, v8, v75
	s_waitcnt lgkmcnt(3)
	v_add_f32_e32 v72, v72, v76
	s_waitcnt lgkmcnt(2)
	v_add_f32_e32 v73, v73, v77
	s_waitcnt lgkmcnt(1)
	v_add_f32_e32 v74, v74, v78
	s_waitcnt lgkmcnt(0)
	v_add_f32_e32 v75, v75, v79
	ds_bpermute_b32 v76, v9, v72
	ds_bpermute_b32 v77, v9, v73
	ds_bpermute_b32 v78, v9, v74
	ds_bpermute_b32 v79, v9, v75
	s_waitcnt lgkmcnt(3)
	v_add_f32_e32 v72, v72, v76
	s_waitcnt lgkmcnt(2)
	v_add_f32_e32 v73, v73, v77
	s_waitcnt lgkmcnt(1)
	v_add_f32_e32 v74, v74, v78
	s_waitcnt lgkmcnt(0)
	v_add_f32_e32 v75, v75, v79
	ds_bpermute_b32 v76, v10, v72
	ds_bpermute_b32 v77, v10, v73
	ds_bpermute_b32 v78, v10, v74
	ds_bpermute_b32 v79, v10, v75
	s_waitcnt lgkmcnt(3)
	v_add_f32_e32 v72, v72, v76
	s_waitcnt lgkmcnt(2)
	v_add_f32_e32 v73, v73, v77
	s_waitcnt lgkmcnt(1)
	v_add_f32_e32 v74, v74, v78
	s_waitcnt lgkmcnt(0)
	v_add_f32_e32 v75, v75, v79
	ds_bpermute_b32 v76, v11, v72
	ds_bpermute_b32 v77, v11, v73
	ds_bpermute_b32 v78, v11, v74
	ds_bpermute_b32 v79, v11, v75
	s_waitcnt lgkmcnt(3)
	v_add_f32_e32 v72, v72, v76
	s_waitcnt lgkmcnt(2)
	v_add_f32_e32 v73, v73, v77
	s_waitcnt lgkmcnt(1)
	v_add_f32_e32 v74, v74, v78
	s_waitcnt lgkmcnt(0)
	v_add_f32_e32 v75, v75, v79
	ds_bpermute_b32 v76, v12, v72
	ds_bpermute_b32 v77, v12, v73
	ds_bpermute_b32 v78, v12, v74
	ds_bpermute_b32 v79, v12, v75
	s_waitcnt lgkmcnt(3)
	v_add_f32_e32 v72, v72, v76
	s_waitcnt lgkmcnt(2)
	v_add_f32_e32 v73, v73, v77
	s_waitcnt lgkmcnt(1)
	v_add_f32_e32 v74, v74, v78
	s_waitcnt lgkmcnt(0)
	v_add_f32_e32 v75, v75, v79
	ds_bpermute_b32 v76, v13, v72
	ds_bpermute_b32 v77, v13, v73
	ds_bpermute_b32 v78, v13, v74
	ds_bpermute_b32 v79, v13, v75
	s_waitcnt lgkmcnt(3)
	v_add_f32_e32 v72, v72, v76
	s_waitcnt lgkmcnt(2)
	v_add_f32_e32 v73, v73, v77
	s_waitcnt lgkmcnt(1)
	v_add_f32_e32 v74, v74, v78
	s_waitcnt lgkmcnt(0)
	v_add_f32_e32 v75, v75, v79
	v_fmamk_f32 v80, v72, 0x3c000000, v14
	v_mul_f32_e32 v76, 0x4b800000, v80
	v_cmp_gt_f32_e32 vcc, s14, v80
	s_nop 1
	v_cndmask_b32_e32 v80, v80, v76, vcc
	v_rsq_f32_e32 v80, v80
	s_nop 0
	v_mul_f32_e32 v76, 0x45800000, v80
	v_cndmask_b32_e32 v80, v80, v76, vcc
	v_mul_f32_e32 v64, v64, v80
	v_mul_f32_e32 v68, v68, v80
	v_mul_f32_e32 v64, v2, v64
	v_mul_f32_e32 v68, v3, v68
	v_lshlrev_b32_e32 v76, 16, v136
	v_and_b32_e32 v72, 0xffff0000, v136
	v_mul_f32_e32 v64, v64, v76
	v_mul_f32_e32 v68, v68, v72
	v_cvt_pk_bf16_f32 v64, v64, v68
	global_store_dword v[98:99], v64, off nt
	v_fmamk_f32 v81, v73, 0x3c000000, v14
	v_mul_f32_e32 v77, 0x4b800000, v81
	v_cmp_gt_f32_e32 vcc, s14, v81
	s_nop 1
	v_cndmask_b32_e32 v81, v81, v77, vcc
	v_rsq_f32_e32 v81, v81
	s_nop 0
	v_mul_f32_e32 v77, 0x45800000, v81
	v_cndmask_b32_e32 v81, v81, v77, vcc
	v_mul_f32_e32 v65, v65, v81
	v_mul_f32_e32 v69, v69, v81
	v_mul_f32_e32 v65, v2, v65
	v_mul_f32_e32 v69, v3, v69
	v_lshlrev_b32_e32 v77, 16, v137
	v_and_b32_e32 v73, 0xffff0000, v137
	v_mul_f32_e32 v65, v65, v77
	v_mul_f32_e32 v69, v69, v73
	v_cvt_pk_bf16_f32 v65, v65, v69
	global_store_dword v[98:99], v65, off offset:256 nt
	v_fmamk_f32 v82, v74, 0x3c000000, v14
	v_mul_f32_e32 v78, 0x4b800000, v82
	v_cmp_gt_f32_e32 vcc, s14, v82
	s_nop 1
	v_cndmask_b32_e32 v82, v82, v78, vcc
	v_rsq_f32_e32 v82, v82
	s_nop 0
	v_mul_f32_e32 v78, 0x45800000, v82
	v_cndmask_b32_e32 v82, v82, v78, vcc
	v_mul_f32_e32 v66, v66, v82
	v_mul_f32_e32 v70, v70, v82
	v_mul_f32_e32 v66, v2, v66
	v_mul_f32_e32 v70, v3, v70
	v_lshlrev_b32_e32 v78, 16, v138
	v_and_b32_e32 v74, 0xffff0000, v138
	v_mul_f32_e32 v66, v66, v78
	v_mul_f32_e32 v70, v70, v74
	v_cvt_pk_bf16_f32 v66, v66, v70
	global_store_dword v[98:99], v66, off offset:512 nt
	v_fmamk_f32 v83, v75, 0x3c000000, v14
	v_mul_f32_e32 v79, 0x4b800000, v83
	v_cmp_gt_f32_e32 vcc, s14, v83
	s_nop 1
	v_cndmask_b32_e32 v83, v83, v79, vcc
	v_rsq_f32_e32 v83, v83
	s_nop 0
	v_mul_f32_e32 v79, 0x45800000, v83
	v_cndmask_b32_e32 v83, v83, v79, vcc
	v_mul_f32_e32 v67, v67, v83
	v_mul_f32_e32 v71, v71, v83
	v_mul_f32_e32 v67, v2, v67
	v_mul_f32_e32 v71, v3, v71
	v_lshlrev_b32_e32 v79, 16, v139
	v_and_b32_e32 v75, 0xffff0000, v139
	v_mul_f32_e32 v67, v67, v79
	v_mul_f32_e32 v71, v71, v75
	v_cvt_pk_bf16_f32 v67, v67, v71
	global_store_dword v[98:99], v67, off offset:768 nt
	v_lshl_add_u64 v[98:99], v[98:99], 0, s[16:17]
	s_waitcnt vmcnt(12)
; DI unsigned cvt_pk_bf16(float lo, float hi) { unsigned r; asm("v_cvt_pk_bf16_f32 %0, %1, %2" : "=v"(r) : "v"(lo), "v"(hi)); return r; }
; DI void phase_combine(const Params& p) {
;     ...
;     for (int hh = 0; hh < 4; ++hh) { const size_t idx = ((size_t)tok * 512 + hh * 128 + lane * 2) >> 1; a[hh] = ofw[idx]; b[hh] = obw[idx]; g[hh] = GH[idx]; }
; #pragma unroll
;     for (int hh = 0; hh < 4; ++hh) {
;       const float o0 = __uint_as_float(a[hh] << 16) + __uint_as_float(b[hh] << 16), o1 = __uint_as_float(a[hh] & 0xffff0000u) + __uint_as_float(b[hh] & 0xffff0000u);
;       const float ss = wave_sum(o0 * o0 + o1 * o1);
;       const float rstd = rsqrtf(ss * (1.f / 128.f) + EPSN);
;       const float g0 = __uint_as_float(g[hh] << 16), g1 = __uint_as_float(g[hh] & 0xffff0000u);
;       *(unsigned*)(OC + (size_t)tok * 1024 + 512 + hh * 128 + lane * 2) = cvt_pk_bf16(o0 * rstd * w0 * g0, o1 * rstd * w1 * g1);
;     }
	v_lshlrev_b32_e32 v64, 16, v140
	v_lshlrev_b32_e32 v76, 16, v144
	v_and_b32_e32 v68, 0xffff0000, v140
	v_and_b32_e32 v80, 0xffff0000, v144
	v_add_f32_e32 v64, v64, v76
	v_add_f32_e32 v68, v68, v80
	v_mul_f32_e32 v72, v64, v64
	v_mul_f32_e32 v76, v68, v68
	v_add_f32_e32 v72, v72, v76
	v_lshlrev_b32_e32 v65, 16, v141
	v_lshlrev_b32_e32 v77, 16, v145
	v_and_b32_e32 v69, 0xffff0000, v141
	v_and_b32_e32 v81, 0xffff0000, v145
	v_add_f32_e32 v65, v65, v77
	v_add_f32_e32 v69, v69, v81
	v_mul_f32_e32 v73, v65, v65
	v_mul_f32_e32 v77, v69, v69
	v_add_f32_e32 v73, v73, v77
	v_lshlrev_b32_e32 v66, 16, v142
	v_lshlrev_b32_e32 v78, 16, v146
	v_and_b32_e32 v70, 0xffff0000, v142
	v_and_b32_e32 v82, 0xffff0000, v146
	v_add_f32_e32 v66, v66, v78
	v_add_f32_e32 v70, v70, v82
	v_mul_f32_e32 v74, v66, v66
	v_mul_f32_e32 v78, v70, v70
	v_add_f32_e32 v74, v74, v78
	v_lshlrev_b32_e32 v67, 16, v143
	v_lshlrev_b32_e32 v79, 16, v147
	v_and_b32_e32 v71, 0xffff0000, v143
	v_and_b32_e32 v83, 0xffff0000, v147
	v_add_f32_e32 v67, v67, v79
	v_add_f32_e32 v71, v71, v83
	v_mul_f32_e32 v75, v67, v67
	v_mul_f32_e32 v79, v71, v71
	v_add_f32_e32 v75, v75, v79
	ds_bpermute_b32 v76, v8, v72
	ds_bpermute_b32 v77, v8, v73
	ds_bpermute_b32 v78, v8, v74
	ds_bpermute_b32 v79, v8, v75
	s_waitcnt lgkmcnt(3)
	v_add_f32_e32 v72, v72, v76
	s_waitcnt lgkmcnt(2)
	v_add_f32_e32 v73, v73, v77
	s_waitcnt lgkmcnt(1)
	v_add_f32_e32 v74, v74, v78
	s_waitcnt lgkmcnt(0)
	v_add_f32_e32 v75, v75, v79
	ds_bpermute_b32 v76, v9, v72
	ds_bpermute_b32 v77, v9, v73
	ds_bpermute_b32 v78, v9, v74
	ds_bpermute_b32 v79, v9, v75
	s_waitcnt lgkmcnt(3)
	v_add_f32_e32 v72, v72, v76
	s_waitcnt lgkmcnt(2)
	v_add_f32_e32 v73, v73, v77
	s_waitcnt lgkmcnt(1)
	v_add_f32_e32 v74, v74, v78
	s_waitcnt lgkmcnt(0)
	v_add_f32_e32 v75, v75, v79
	ds_bpermute_b32 v76, v10, v72
	ds_bpermute_b32 v77, v10, v73
	ds_bpermute_b32 v78, v10, v74
	ds_bpermute_b32 v79, v10, v75
	s_waitcnt lgkmcnt(3)
	v_add_f32_e32 v72, v72, v76
	s_waitcnt lgkmcnt(2)
	v_add_f32_e32 v73, v73, v77
	s_waitcnt lgkmcnt(1)
	v_add_f32_e32 v74, v74, v78
	s_waitcnt lgkmcnt(0)
	v_add_f32_e32 v75, v75, v79
	ds_bpermute_b32 v76, v11, v72
	ds_bpermute_b32 v77, v11, v73
	ds_bpermute_b32 v78, v11, v74
	ds_bpermute_b32 v79, v11, v75
	s_waitcnt lgkmcnt(3)
	v_add_f32_e32 v72, v72, v76
	s_waitcnt lgkmcnt(2)
	v_add_f32_e32 v73, v73, v77
	s_waitcnt lgkmcnt(1)
	v_add_f32_e32 v74, v74, v78
	s_waitcnt lgkmcnt(0)
	v_add_f32_e32 v75, v75, v79
	ds_bpermute_b32 v76, v12, v72
	ds_bpermute_b32 v77, v12, v73
	ds_bpermute_b32 v78, v12, v74
	ds_bpermute_b32 v79, v12, v75
	s_waitcnt lgkmcnt(3)
	v_add_f32_e32 v72, v72, v76
	s_waitcnt lgkmcnt(2)
	v_add_f32_e32 v73, v73, v77
	s_waitcnt lgkmcnt(1)
	v_add_f32_e32 v74, v74, v78
	s_waitcnt lgkmcnt(0)
	v_add_f32_e32 v75, v75, v79
	ds_bpermute_b32 v76, v13, v72
	ds_bpermute_b32 v77, v13, v73
	ds_bpermute_b32 v78, v13, v74
	ds_bpermute_b32 v79, v13, v75
	s_waitcnt lgkmcnt(3)
	v_add_f32_e32 v72, v72, v76
	s_waitcnt lgkmcnt(2)
	v_add_f32_e32 v73, v73, v77
	s_waitcnt lgkmcnt(1)
	v_add_f32_e32 v74, v74, v78
	s_waitcnt lgkmcnt(0)
	v_add_f32_e32 v75, v75, v79
	v_fmamk_f32 v80, v72, 0x3c000000, v14
	v_mul_f32_e32 v76, 0x4b800000, v80
	v_cmp_gt_f32_e32 vcc, s14, v80
	s_nop 1
	v_cndmask_b32_e32 v80, v80, v76, vcc
	v_rsq_f32_e32 v80, v80
	s_nop 0
	v_mul_f32_e32 v76, 0x45800000, v80
	v_cndmask_b32_e32 v80, v80, v76, vcc
	v_mul_f32_e32 v64, v64, v80
	v_mul_f32_e32 v68, v68, v80
	v_mul_f32_e32 v64, v2, v64
	v_mul_f32_e32 v68, v3, v68
	v_lshlrev_b32_e32 v76, 16, v148
	v_and_b32_e32 v72, 0xffff0000, v148
	v_mul_f32_e32 v64, v64, v76
	v_mul_f32_e32 v68, v68, v72
	v_cvt_pk_bf16_f32 v64, v64, v68
	global_store_dword v[98:99], v64, off nt
	v_fmamk_f32 v81, v73, 0x3c000000, v14
	v_mul_f32_e32 v77, 0x4b800000, v81
	v_cmp_gt_f32_e32 vcc, s14, v81
	s_nop 1
	v_cndmask_b32_e32 v81, v81, v77, vcc
	v_rsq_f32_e32 v81, v81
	s_nop 0
	v_mul_f32_e32 v77, 0x45800000, v81
	v_cndmask_b32_e32 v81, v81, v77, vcc
	v_mul_f32_e32 v65, v65, v81
	v_mul_f32_e32 v69, v69, v81
	v_mul_f32_e32 v65, v2, v65
	v_mul_f32_e32 v69, v3, v69
	v_lshlrev_b32_e32 v77, 16, v149
	v_and_b32_e32 v73, 0xffff0000, v149
	v_mul_f32_e32 v65, v65, v77
	v_mul_f32_e32 v69, v69, v73
	v_cvt_pk_bf16_f32 v65, v65, v69
	global_store_dword v[98:99], v65, off offset:256 nt
	v_fmamk_f32 v82, v74, 0x3c000000, v14
	v_mul_f32_e32 v78, 0x4b800000, v82
	v_cmp_gt_f32_e32 vcc, s14, v82
	s_nop 1
	v_cndmask_b32_e32 v82, v82, v78, vcc
	v_rsq_f32_e32 v82, v82
	s_nop 0
	v_mul_f32_e32 v78, 0x45800000, v82
	v_cndmask_b32_e32 v82, v82, v78, vcc
	v_mul_f32_e32 v66, v66, v82
	v_mul_f32_e32 v70, v70, v82
	v_mul_f32_e32 v66, v2, v66
	v_mul_f32_e32 v70, v3, v70
	v_lshlrev_b32_e32 v78, 16, v150
	v_and_b32_e32 v74, 0xffff0000, v150
	v_mul_f32_e32 v66, v66, v78
	v_mul_f32_e32 v70, v70, v74
	v_cvt_pk_bf16_f32 v66, v66, v70
	global_store_dword v[98:99], v66, off offset:512 nt
	v_fmamk_f32 v83, v75, 0x3c000000, v14
	v_mul_f32_e32 v79, 0x4b800000, v83
	v_cmp_gt_f32_e32 vcc, s14, v83
	s_nop 1
	v_cndmask_b32_e32 v83, v83, v79, vcc
	v_rsq_f32_e32 v83, v83
	s_nop 0
	v_mul_f32_e32 v79, 0x45800000, v83
	v_cndmask_b32_e32 v83, v83, v79, vcc
	v_mul_f32_e32 v67, v67, v83
	v_mul_f32_e32 v71, v71, v83
	v_mul_f32_e32 v67, v2, v67
	v_mul_f32_e32 v71, v3, v71
	v_lshlrev_b32_e32 v79, 16, v151
	v_and_b32_e32 v75, 0xffff0000, v151
	v_mul_f32_e32 v67, v67, v79
	v_mul_f32_e32 v71, v71, v75
	v_cvt_pk_bf16_f32 v67, v67, v71
	global_store_dword v[98:99], v67, off offset:768 nt
	v_lshl_add_u64 v[98:99], v[98:99], 0, s[16:17]
	s_branch .LBB0_952
